# peel first K-tile pair: zero C operand instead of 128 v_mov per unit (on top of mfma pairs)
# speedup vs baseline: 1.0018x; 1.0018x over previous
.LBB0_224:
	s_add_u32 s33, s16, 0x100
	s_addc_u32 s42, s17, 0
	s_mov_b32 s18, -2
	s_mov_b64 s[4:5], 0
	s_add_i32 s43, s18, 2
	s_lshr_b32 s44, s43, 2
	s_add_i32 s16, s18, 4
	s_lshl_b64 s[60:61], s[44:45], 9
	s_lshr_b32 s44, s16, 2
	s_and_b32 s47, s4, 0x100
	s_lshl_b64 s[16:17], s[44:45], 9
	s_add_u32 s19, s14, s16
	s_addc_u32 s44, s15, s17
	s_add_u32 s16, s4, 0x100
	s_addc_u32 s17, s5, 0
	s_and_b32 s49, s16, 0x100
	s_add_u32 s49, s19, s49
	s_addc_u32 s19, s44, 0
	s_add_u32 s4, s33, s4
	s_addc_u32 s5, s42, s5
	s_add_i32 s44, 0, 0x10000
	s_add_u32 s59, s14, s60
	s_addc_u32 s60, s15, s61
	s_cmp_eq_u32 s18, 28
	s_cselect_b32 s19, s11, s19
	s_cselect_b32 s18, s10, s49
	s_cselect_b32 s5, s13, s5
	s_cselect_b32 s4, s12, s4
	s_add_i32 s49, 0, 0x14000
	v_add_u32_e32 v154, s44, v152
	v_add_u32_e32 v170, s49, v152
	ds_read_b128 v[140:143], v154
	ds_read_b128 v[144:147], v154 offset:1024
	ds_read_b128 v[148:151], v154 offset:2048
	ds_read_b128 v[154:157], v154 offset:3072
	ds_read_b128 v[158:161], v170
	ds_read_b128 v[162:165], v170 offset:1024
	ds_read_b128 v[166:169], v170 offset:2048
	ds_read_b128 v[170:173], v170 offset:3072
	s_add_u32 s47, s59, s47
	s_addc_u32 s59, s60, 0
	s_add_u32 s60, s47, 0x80080
	s_addc_u32 s61, s59, 0
	v_lshl_add_u64 v[194:195], s[60:61], 0, v[130:131]
	s_add_i32 m0, s27, 0xc000
	ds_read_b128 v[174:177], v153
	ds_read_b128 v[178:181], v153 offset:1024
	ds_read_b128 v[182:185], v153 offset:2048
	ds_read_b128 v[186:189], v153 offset:3072
	ds_read_b128 v[190:193], v153 offset:4096
	ds_read_b128 v[198:201], v153 offset:5120
	ds_read_b128 v[202:205], v153 offset:6144
	ds_read_b128 v[206:209], v153 offset:7168
	global_load_lds_dwordx4 v[194:195], off
	v_lshl_add_u64 v[194:195], s[60:61], 0, v[134:135]
	s_add_i32 m0, s27, 0xe000
	s_nop 0
	global_load_lds_dwordx4 v[194:195], off
	s_waitcnt vmcnt(8)
	s_waitcnt lgkmcnt(0)
	s_barrier
	s_setprio 1
	s_waitcnt lgkmcnt(0)
	v_mfma_f32_16x16x32_bf16 v[126:129], v[140:143], v[174:177], 0
	v_mfma_f32_16x16x32_bf16 v[126:129], v[144:147], v[178:181], v[126:129]
	v_mfma_f32_16x16x32_bf16 v[122:125], v[148:151], v[174:177], 0
	v_mfma_f32_16x16x32_bf16 v[122:125], v[154:157], v[178:181], v[122:125]
	v_mfma_f32_16x16x32_bf16 v[110:113], v[140:143], v[182:185], 0
	v_mfma_f32_16x16x32_bf16 v[110:113], v[144:147], v[186:189], v[110:113]
	v_mfma_f32_16x16x32_bf16 v[106:109], v[148:151], v[182:185], 0
	v_mfma_f32_16x16x32_bf16 v[106:109], v[154:157], v[186:189], v[106:109]
	v_mfma_f32_16x16x32_bf16 v[94:97], v[140:143], v[190:193], 0
	v_mfma_f32_16x16x32_bf16 v[94:97], v[144:147], v[198:201], v[94:97]
	v_mfma_f32_16x16x32_bf16 v[90:93], v[148:151], v[190:193], 0
	v_mfma_f32_16x16x32_bf16 v[90:93], v[154:157], v[198:201], v[90:93]
	v_mfma_f32_16x16x32_bf16 v[78:81], v[140:143], v[202:205], 0
	v_mfma_f32_16x16x32_bf16 v[78:81], v[144:147], v[206:209], v[78:81]
	v_mfma_f32_16x16x32_bf16 v[74:77], v[148:151], v[202:205], 0
	v_mfma_f32_16x16x32_bf16 v[74:77], v[154:157], v[206:209], v[74:77]
	s_setprio 0
	s_setprio 1
	v_mfma_f32_16x16x32_bf16 v[118:121], v[158:161], v[174:177], 0
	v_mfma_f32_16x16x32_bf16 v[118:121], v[162:165], v[178:181], v[118:121]
	v_mfma_f32_16x16x32_bf16 v[114:117], v[166:169], v[174:177], 0
	v_mfma_f32_16x16x32_bf16 v[114:117], v[170:173], v[178:181], v[114:117]
	v_mfma_f32_16x16x32_bf16 v[102:105], v[158:161], v[182:185], 0
	v_mfma_f32_16x16x32_bf16 v[102:105], v[162:165], v[186:189], v[102:105]
	v_mfma_f32_16x16x32_bf16 v[98:101], v[166:169], v[182:185], 0
	v_mfma_f32_16x16x32_bf16 v[98:101], v[170:173], v[186:189], v[98:101]
	v_mfma_f32_16x16x32_bf16 v[86:89], v[158:161], v[190:193], 0
	v_mfma_f32_16x16x32_bf16 v[86:89], v[162:165], v[198:201], v[86:89]
	v_mfma_f32_16x16x32_bf16 v[82:85], v[166:169], v[190:193], 0
	v_mfma_f32_16x16x32_bf16 v[82:85], v[170:173], v[198:201], v[82:85]
	v_mfma_f32_16x16x32_bf16 v[70:73], v[158:161], v[202:205], 0
	v_mfma_f32_16x16x32_bf16 v[70:73], v[162:165], v[206:209], v[70:73]
	v_mfma_f32_16x16x32_bf16 v[66:69], v[166:169], v[202:205], 0
	v_mfma_f32_16x16x32_bf16 v[66:69], v[170:173], v[206:209], v[66:69]
	s_setprio 0
	s_barrier
	s_add_i32 s44, s44, s9
	v_lshl_add_u64 v[194:195], s[4:5], 0, v[132:133]
	s_mov_b32 m0, s44
	ds_read_b128 v[174:177], v153 offset:16384
	ds_read_b128 v[178:181], v153 offset:17408
	ds_read_b128 v[182:185], v153 offset:18432
	ds_read_b128 v[186:189], v153 offset:19456
	ds_read_b128 v[190:193], v153 offset:20480
	ds_read_b128 v[198:201], v153 offset:21504
	ds_read_b128 v[202:205], v153 offset:22528
	ds_read_b128 v[206:209], v153 offset:23552
	global_load_lds_dwordx4 v[194:195], off
	s_add_i32 m0, s44, 0x2000
	s_add_u32 s60, s4, 0x80000
	v_lshl_add_u64 v[210:211], s[4:5], 0, v[136:137]
	s_addc_u32 s61, s5, 0
	s_add_i32 s44, s49, s9
	global_load_lds_dwordx4 v[210:211], off
	v_lshl_add_u64 v[212:213], s[60:61], 0, v[132:133]
	s_mov_b32 m0, s44
	v_lshl_add_u64 v[214:215], s[18:19], 0, v[134:135]
	global_load_lds_dwordx4 v[212:213], off
	v_lshl_add_u64 v[212:213], s[60:61], 0, v[136:137]
	s_add_i32 m0, s44, 0x2000
	s_nop 0
	global_load_lds_dwordx4 v[212:213], off
	v_lshl_add_u64 v[212:213], s[18:19], 0, v[130:131]
	s_mov_b32 m0, s27
	s_nop 0
	global_load_lds_dwordx4 v[212:213], off
	s_mov_b32 m0, s28
	s_nop 0
	global_load_lds_dwordx4 v[214:215], off
	s_waitcnt vmcnt(8)
	s_waitcnt lgkmcnt(0)
	s_barrier
	s_setprio 1
	s_waitcnt lgkmcnt(0)
	v_mfma_f32_16x16x32_bf16 v[62:65], v[140:143], v[174:177], 0
	v_mfma_f32_16x16x32_bf16 v[62:65], v[144:147], v[178:181], v[62:65]
	v_mfma_f32_16x16x32_bf16 v[58:61], v[148:151], v[174:177], 0
	v_mfma_f32_16x16x32_bf16 v[58:61], v[154:157], v[178:181], v[58:61]
	v_mfma_f32_16x16x32_bf16 v[46:49], v[140:143], v[182:185], 0
	v_mfma_f32_16x16x32_bf16 v[46:49], v[144:147], v[186:189], v[46:49]
	v_mfma_f32_16x16x32_bf16 v[42:45], v[148:151], v[182:185], 0
	v_mfma_f32_16x16x32_bf16 v[42:45], v[154:157], v[186:189], v[42:45]
	v_mfma_f32_16x16x32_bf16 v[30:33], v[140:143], v[190:193], 0
	v_mfma_f32_16x16x32_bf16 v[30:33], v[144:147], v[198:201], v[30:33]
	v_mfma_f32_16x16x32_bf16 v[26:29], v[148:151], v[190:193], 0
	v_mfma_f32_16x16x32_bf16 v[26:29], v[154:157], v[198:201], v[26:29]
	v_mfma_f32_16x16x32_bf16 v[14:17], v[140:143], v[202:205], 0
	v_mfma_f32_16x16x32_bf16 v[14:17], v[144:147], v[206:209], v[14:17]
	v_mfma_f32_16x16x32_bf16 v[10:13], v[148:151], v[202:205], 0
	v_mfma_f32_16x16x32_bf16 v[10:13], v[154:157], v[206:209], v[10:13]
	s_setprio 0
	s_setprio 1
	v_mfma_f32_16x16x32_bf16 v[54:57], v[158:161], v[174:177], 0
	v_mfma_f32_16x16x32_bf16 v[54:57], v[162:165], v[178:181], v[54:57]
	v_mfma_f32_16x16x32_bf16 v[50:53], v[166:169], v[174:177], 0
	v_mfma_f32_16x16x32_bf16 v[50:53], v[170:173], v[178:181], v[50:53]
	v_mfma_f32_16x16x32_bf16 v[38:41], v[158:161], v[182:185], 0
	v_mfma_f32_16x16x32_bf16 v[38:41], v[162:165], v[186:189], v[38:41]
	v_mfma_f32_16x16x32_bf16 v[34:37], v[166:169], v[182:185], 0
	v_mfma_f32_16x16x32_bf16 v[34:37], v[170:173], v[186:189], v[34:37]
	v_mfma_f32_16x16x32_bf16 v[22:25], v[158:161], v[190:193], 0
	v_mfma_f32_16x16x32_bf16 v[22:25], v[162:165], v[198:201], v[22:25]
	v_mfma_f32_16x16x32_bf16 v[18:21], v[166:169], v[190:193], 0
	v_mfma_f32_16x16x32_bf16 v[18:21], v[170:173], v[198:201], v[18:21]
	v_mfma_f32_16x16x32_bf16 v[6:9], v[158:161], v[202:205], 0
	v_mfma_f32_16x16x32_bf16 v[6:9], v[162:165], v[206:209], v[6:9]
	v_mfma_f32_16x16x32_bf16 v[2:5], v[166:169], v[202:205], 0
	v_mfma_f32_16x16x32_bf16 v[2:5], v[170:173], v[206:209], v[2:5]
	s_setprio 0
	s_barrier
	s_add_i32 s44, 0, 0x18000
	s_add_i32 s47, 0, 0x1c000
	v_add_u32_e32 v154, s44, v152
	v_add_u32_e32 v170, s47, v152
	ds_read_b128 v[140:143], v154
	ds_read_b128 v[144:147], v154 offset:1024
	ds_read_b128 v[148:151], v154 offset:2048
	ds_read_b128 v[154:157], v154 offset:3072
	ds_read_b128 v[158:161], v170
	ds_read_b128 v[162:165], v170 offset:1024
	ds_read_b128 v[166:169], v170 offset:2048
	ds_read_b128 v[170:173], v170 offset:3072
	s_add_u32 s18, s18, 0x80000
	s_addc_u32 s19, s19, 0
	s_mov_b32 m0, s29
	v_lshl_add_u64 v[216:217], s[18:19], 0, v[130:131]
	ds_read_b128 v[174:177], v153 offset:32768
	ds_read_b128 v[178:181], v153 offset:33792
	ds_read_b128 v[182:185], v153 offset:34816
	ds_read_b128 v[186:189], v153 offset:35840
	ds_read_b128 v[190:193], v153 offset:36864
	ds_read_b128 v[198:201], v153 offset:37888
	ds_read_b128 v[202:205], v153 offset:38912
	ds_read_b128 v[206:209], v153 offset:39936
	global_load_lds_dwordx4 v[216:217], off
	v_lshl_add_u64 v[216:217], s[18:19], 0, v[134:135]
	s_mov_b32 m0, s30
	s_nop 0
	global_load_lds_dwordx4 v[216:217], off
	s_waitcnt vmcnt(8)
	s_waitcnt lgkmcnt(0)
	s_barrier
	s_setprio 1
	s_waitcnt lgkmcnt(0)
	v_mfma_f32_16x16x32_bf16 v[126:129], v[140:143], v[174:177], v[126:129]
	v_mfma_f32_16x16x32_bf16 v[126:129], v[144:147], v[178:181], v[126:129]
	v_mfma_f32_16x16x32_bf16 v[122:125], v[148:151], v[174:177], v[122:125]
	v_mfma_f32_16x16x32_bf16 v[122:125], v[154:157], v[178:181], v[122:125]
	v_mfma_f32_16x16x32_bf16 v[110:113], v[140:143], v[182:185], v[110:113]
	v_mfma_f32_16x16x32_bf16 v[110:113], v[144:147], v[186:189], v[110:113]
	v_mfma_f32_16x16x32_bf16 v[106:109], v[148:151], v[182:185], v[106:109]
	v_mfma_f32_16x16x32_bf16 v[106:109], v[154:157], v[186:189], v[106:109]
	v_mfma_f32_16x16x32_bf16 v[94:97], v[140:143], v[190:193], v[94:97]
	v_mfma_f32_16x16x32_bf16 v[94:97], v[144:147], v[198:201], v[94:97]
	v_mfma_f32_16x16x32_bf16 v[90:93], v[148:151], v[190:193], v[90:93]
	v_mfma_f32_16x16x32_bf16 v[90:93], v[154:157], v[198:201], v[90:93]
	v_mfma_f32_16x16x32_bf16 v[78:81], v[140:143], v[202:205], v[78:81]
	v_mfma_f32_16x16x32_bf16 v[78:81], v[144:147], v[206:209], v[78:81]
	v_mfma_f32_16x16x32_bf16 v[74:77], v[148:151], v[202:205], v[74:77]
	v_mfma_f32_16x16x32_bf16 v[74:77], v[154:157], v[206:209], v[74:77]
	s_setprio 0
	s_setprio 1
	v_mfma_f32_16x16x32_bf16 v[118:121], v[158:161], v[174:177], v[118:121]
	v_mfma_f32_16x16x32_bf16 v[118:121], v[162:165], v[178:181], v[118:121]
	v_mfma_f32_16x16x32_bf16 v[114:117], v[166:169], v[174:177], v[114:117]
	v_mfma_f32_16x16x32_bf16 v[114:117], v[170:173], v[178:181], v[114:117]
	v_mfma_f32_16x16x32_bf16 v[102:105], v[158:161], v[182:185], v[102:105]
	v_mfma_f32_16x16x32_bf16 v[102:105], v[162:165], v[186:189], v[102:105]
	v_mfma_f32_16x16x32_bf16 v[98:101], v[166:169], v[182:185], v[98:101]
	v_mfma_f32_16x16x32_bf16 v[98:101], v[170:173], v[186:189], v[98:101]
	v_mfma_f32_16x16x32_bf16 v[86:89], v[158:161], v[190:193], v[86:89]
	v_mfma_f32_16x16x32_bf16 v[86:89], v[162:165], v[198:201], v[86:89]
	v_mfma_f32_16x16x32_bf16 v[82:85], v[166:169], v[190:193], v[82:85]
	v_mfma_f32_16x16x32_bf16 v[82:85], v[170:173], v[198:201], v[82:85]
	v_mfma_f32_16x16x32_bf16 v[70:73], v[158:161], v[202:205], v[70:73]
	v_mfma_f32_16x16x32_bf16 v[70:73], v[162:165], v[206:209], v[70:73]
	v_mfma_f32_16x16x32_bf16 v[66:69], v[166:169], v[202:205], v[66:69]
	v_mfma_f32_16x16x32_bf16 v[66:69], v[170:173], v[206:209], v[66:69]
	s_setprio 0
	s_barrier
	s_add_i32 s18, s44, s9
	v_lshl_add_u64 v[194:195], v[194:195], 0, s[2:3]
	s_mov_b32 m0, s18
	ds_read_b128 v[174:177], v153 offset:49152
	ds_read_b128 v[178:181], v153 offset:50176
	ds_read_b128 v[182:185], v153 offset:51200
	ds_read_b128 v[186:189], v153 offset:52224
	ds_read_b128 v[190:193], v153 offset:53248
	ds_read_b128 v[198:201], v153 offset:54272
	ds_read_b128 v[202:205], v153 offset:55296
	ds_read_b128 v[206:209], v153 offset:56320
	global_load_lds_dwordx4 v[194:195], off
	s_add_i32 m0, s18, 0x2000
	s_add_u32 s4, s4, 0x80080
	v_lshl_add_u64 v[194:195], v[210:211], 0, s[2:3]
	s_addc_u32 s5, s5, 0
	s_add_i32 s18, s47, s9
	global_load_lds_dwordx4 v[194:195], off
	v_lshl_add_u64 v[194:195], s[4:5], 0, v[132:133]
	s_mov_b32 m0, s18
	s_nop 0
	global_load_lds_dwordx4 v[194:195], off
	v_lshl_add_u64 v[194:195], s[4:5], 0, v[136:137]
	s_add_i32 m0, s18, 0x2000
	s_nop 0
	global_load_lds_dwordx4 v[194:195], off
	v_lshl_add_u64 v[194:195], v[212:213], 0, s[2:3]
	s_mov_b32 m0, s51
	s_nop 0
	global_load_lds_dwordx4 v[194:195], off
	v_lshl_add_u64 v[194:195], v[214:215], 0, s[2:3]
	s_mov_b32 m0, s52
	s_nop 0
	global_load_lds_dwordx4 v[194:195], off
	s_waitcnt vmcnt(8)
	s_waitcnt lgkmcnt(0)
	s_barrier
	s_setprio 1
	s_waitcnt lgkmcnt(0)
	v_mfma_f32_16x16x32_bf16 v[62:65], v[140:143], v[174:177], v[62:65]
	v_mfma_f32_16x16x32_bf16 v[62:65], v[144:147], v[178:181], v[62:65]
	v_mfma_f32_16x16x32_bf16 v[58:61], v[148:151], v[174:177], v[58:61]
	v_mfma_f32_16x16x32_bf16 v[58:61], v[154:157], v[178:181], v[58:61]
	v_mfma_f32_16x16x32_bf16 v[46:49], v[140:143], v[182:185], v[46:49]
	v_mfma_f32_16x16x32_bf16 v[46:49], v[144:147], v[186:189], v[46:49]
	v_mfma_f32_16x16x32_bf16 v[42:45], v[148:151], v[182:185], v[42:45]
	v_mfma_f32_16x16x32_bf16 v[42:45], v[154:157], v[186:189], v[42:45]
	v_mfma_f32_16x16x32_bf16 v[30:33], v[140:143], v[190:193], v[30:33]
	v_mfma_f32_16x16x32_bf16 v[30:33], v[144:147], v[198:201], v[30:33]
	v_mfma_f32_16x16x32_bf16 v[26:29], v[148:151], v[190:193], v[26:29]
	v_mfma_f32_16x16x32_bf16 v[26:29], v[154:157], v[198:201], v[26:29]
	v_mfma_f32_16x16x32_bf16 v[14:17], v[140:143], v[202:205], v[14:17]
	v_mfma_f32_16x16x32_bf16 v[14:17], v[144:147], v[206:209], v[14:17]
	v_mfma_f32_16x16x32_bf16 v[10:13], v[148:151], v[202:205], v[10:13]
	v_mfma_f32_16x16x32_bf16 v[10:13], v[154:157], v[206:209], v[10:13]
	s_setprio 0
	s_setprio 1
	v_mfma_f32_16x16x32_bf16 v[54:57], v[158:161], v[174:177], v[54:57]
	v_mfma_f32_16x16x32_bf16 v[54:57], v[162:165], v[178:181], v[54:57]
	v_mfma_f32_16x16x32_bf16 v[50:53], v[166:169], v[174:177], v[50:53]
	v_mfma_f32_16x16x32_bf16 v[50:53], v[170:173], v[178:181], v[50:53]
	v_mfma_f32_16x16x32_bf16 v[38:41], v[158:161], v[182:185], v[38:41]
	v_mfma_f32_16x16x32_bf16 v[38:41], v[162:165], v[186:189], v[38:41]
	v_mfma_f32_16x16x32_bf16 v[34:37], v[166:169], v[182:185], v[34:37]
	v_mfma_f32_16x16x32_bf16 v[34:37], v[170:173], v[186:189], v[34:37]
	v_mfma_f32_16x16x32_bf16 v[22:25], v[158:161], v[190:193], v[22:25]
	v_mfma_f32_16x16x32_bf16 v[22:25], v[162:165], v[198:201], v[22:25]
	v_mfma_f32_16x16x32_bf16 v[18:21], v[166:169], v[190:193], v[18:21]
	v_mfma_f32_16x16x32_bf16 v[18:21], v[170:173], v[198:201], v[18:21]
	v_mfma_f32_16x16x32_bf16 v[6:9], v[158:161], v[202:205], v[6:9]
	v_mfma_f32_16x16x32_bf16 v[6:9], v[162:165], v[206:209], v[6:9]
	v_mfma_f32_16x16x32_bf16 v[2:5], v[166:169], v[202:205], v[2:5]
	v_mfma_f32_16x16x32_bf16 v[2:5], v[170:173], v[206:209], v[2:5]
	s_setprio 0
	s_barrier
	s_cmp_gt_u32 s43, 29
	s_mov_b64 s[4:5], s[16:17]
	s_mov_b32 s18, s43
	s_cbranch_scc1 .Lpeel_exit_proj

.Lpeel_exit_proj:
	s_lshl_b32 s16, s8, 8
	s_add_i32 s16, s16, s50
	s_lshl_b32 s17, s58, 8
	v_or_b32_e32 v140, s16, v139
	s_cmp_gt_i32 s58, 11
	s_mov_b64 s[4:5], -1
	s_cbranch_scc0 .LBB0_267
	s_lshl_b32 s4, s17, 1
	s_add_u32 s4, s6, s4
	s_addc_u32 s5, s7, 0
	v_lshlrev_b32_e32 v196, 1, v138
	v_lshl_add_u64 v[142:143], s[4:5], 0, v[196:197]
	s_mov_b64 s[4:5], 0x2644e800
	v_lshl_add_u64 v[142:143], v[142:143], 0, s[4:5]
	s_cmp_gt_u32 s58, 13
	s_mov_b64 s[4:5], -1
	s_cbranch_scc1 .LBB0_232
	s_movk_i32 s18, 0x3c00
	v_mad_i64_i32 v[148:149], s[4:5], v140, s18, v[142:143]
	v_cvt_pk_bf16_f32 v144, v126, v127
	v_cvt_pk_bf16_f32 v145, v128, v129
	v_cvt_pk_bf16_f32 v146, v122, v123
	v_cvt_pk_bf16_f32 v147, v124, v125
	s_mov_b64 s[14:15], 0x100
	global_store_dwordx4 v[148:149], v[144:147], off sc1
	s_nop 2
	v_cvt_pk_bf16_f32 v144, v118, v119
	v_cvt_pk_bf16_f32 v145, v120, v121
	v_cvt_pk_bf16_f32 v146, v114, v115
	v_cvt_pk_bf16_f32 v147, v116, v117
	v_lshl_add_u64 v[148:149], v[148:149], 0, s[14:15]
	v_or_b32_e32 v141, 16, v140
	global_store_dwordx4 v[148:149], v[144:147], off sc1
	s_nop 2
	v_mad_i64_i32 v[148:149], s[4:5], v141, s18, v[142:143]
	v_cvt_pk_bf16_f32 v144, v110, v111
	v_cvt_pk_bf16_f32 v145, v112, v113
	v_cvt_pk_bf16_f32 v146, v106, v107
	v_cvt_pk_bf16_f32 v147, v108, v109
	v_or_b32_e32 v141, 32, v140
	global_store_dwordx4 v[148:149], v[144:147], off sc1
	s_nop 2
	v_cvt_pk_bf16_f32 v144, v102, v103
	v_cvt_pk_bf16_f32 v145, v104, v105
	v_cvt_pk_bf16_f32 v146, v98, v99
	v_cvt_pk_bf16_f32 v147, v100, v101
	v_lshl_add_u64 v[148:149], v[148:149], 0, s[14:15]
	global_store_dwordx4 v[148:149], v[144:147], off sc1
	s_nop 2
	v_mad_i64_i32 v[148:149], s[4:5], v141, s18, v[142:143]
	v_cvt_pk_bf16_f32 v144, v94, v95
	v_cvt_pk_bf16_f32 v145, v96, v97
	v_cvt_pk_bf16_f32 v146, v90, v91
	v_cvt_pk_bf16_f32 v147, v92, v93
	v_or_b32_e32 v141, 48, v140
	global_store_dwordx4 v[148:149], v[144:147], off sc1
	s_nop 2
	v_cvt_pk_bf16_f32 v144, v86, v87
	v_cvt_pk_bf16_f32 v145, v88, v89
	v_cvt_pk_bf16_f32 v146, v82, v83
	v_cvt_pk_bf16_f32 v147, v84, v85
	v_lshl_add_u64 v[148:149], v[148:149], 0, s[14:15]
	global_store_dwordx4 v[148:149], v[144:147], off sc1
	s_nop 2
	v_mad_i64_i32 v[148:149], s[4:5], v141, s18, v[142:143]
	v_cvt_pk_bf16_f32 v144, v78, v79
	v_cvt_pk_bf16_f32 v145, v80, v81
	v_cvt_pk_bf16_f32 v146, v74, v75
	v_cvt_pk_bf16_f32 v147, v76, v77
	v_add_u32_e32 v141, 0x80, v140
	global_store_dwordx4 v[148:149], v[144:147], off sc1
	s_nop 2
	v_cvt_pk_bf16_f32 v144, v70, v71
	v_cvt_pk_bf16_f32 v145, v72, v73
	v_cvt_pk_bf16_f32 v146, v66, v67
	v_cvt_pk_bf16_f32 v147, v68, v69
	v_lshl_add_u64 v[148:149], v[148:149], 0, s[14:15]
	global_store_dwordx4 v[148:149], v[144:147], off sc1
	s_nop 2
	v_mad_i64_i32 v[148:149], s[4:5], v141, s18, v[142:143]
	v_cvt_pk_bf16_f32 v144, v62, v63
	v_cvt_pk_bf16_f32 v145, v64, v65
	v_cvt_pk_bf16_f32 v146, v58, v59
	v_cvt_pk_bf16_f32 v147, v60, v61
	v_add_u32_e32 v141, 0x90, v140
	global_store_dwordx4 v[148:149], v[144:147], off sc1
	s_nop 2
	v_cvt_pk_bf16_f32 v144, v54, v55
	v_cvt_pk_bf16_f32 v145, v56, v57
	v_cvt_pk_bf16_f32 v146, v50, v51
	v_cvt_pk_bf16_f32 v147, v52, v53
	v_lshl_add_u64 v[148:149], v[148:149], 0, s[14:15]
	global_store_dwordx4 v[148:149], v[144:147], off sc1
	s_nop 2
	v_mad_i64_i32 v[148:149], s[4:5], v141, s18, v[142:143]
	v_cvt_pk_bf16_f32 v144, v46, v47
	v_cvt_pk_bf16_f32 v145, v48, v49
	v_cvt_pk_bf16_f32 v146, v42, v43
	v_cvt_pk_bf16_f32 v147, v44, v45
	v_add_u32_e32 v141, 0xa0, v140
	global_store_dwordx4 v[148:149], v[144:147], off sc1
	s_nop 2
	v_cvt_pk_bf16_f32 v144, v38, v39
	v_cvt_pk_bf16_f32 v145, v40, v41
	v_cvt_pk_bf16_f32 v146, v34, v35
	v_cvt_pk_bf16_f32 v147, v36, v37
	v_lshl_add_u64 v[148:149], v[148:149], 0, s[14:15]
	global_store_dwordx4 v[148:149], v[144:147], off sc1
	s_nop 2
	v_mad_i64_i32 v[148:149], s[4:5], v141, s18, v[142:143]
	v_cvt_pk_bf16_f32 v144, v30, v31
	v_cvt_pk_bf16_f32 v145, v32, v33
	v_cvt_pk_bf16_f32 v146, v26, v27
	v_cvt_pk_bf16_f32 v147, v28, v29
	v_add_u32_e32 v141, 0xb0, v140
	global_store_dwordx4 v[148:149], v[144:147], off sc1
	s_nop 2
	v_cvt_pk_bf16_f32 v144, v22, v23
	v_cvt_pk_bf16_f32 v145, v24, v25
	v_cvt_pk_bf16_f32 v146, v18, v19
	v_cvt_pk_bf16_f32 v147, v20, v21
	v_lshl_add_u64 v[148:149], v[148:149], 0, s[14:15]
	global_store_dwordx4 v[148:149], v[144:147], off sc1
	s_nop 2
	v_mad_i64_i32 v[148:149], s[4:5], v141, s18, v[142:143]
	v_cvt_pk_bf16_f32 v144, v14, v15
	v_cvt_pk_bf16_f32 v145, v16, v17
	v_cvt_pk_bf16_f32 v146, v10, v11
	v_cvt_pk_bf16_f32 v147, v12, v13
	s_movk_i32 s69, 0x3c00
	global_store_dwordx4 v[148:149], v[144:147], off sc1
	s_nop 2
	v_cvt_pk_bf16_f32 v144, v6, v7
	v_cvt_pk_bf16_f32 v145, v8, v9
	v_cvt_pk_bf16_f32 v146, v2, v3
	v_cvt_pk_bf16_f32 v147, v4, v5
	v_lshl_add_u64 v[148:149], v[148:149], 0, s[14:15]
	global_store_dwordx4 v[148:149], v[144:147], off sc1
	s_nop 2
	s_waitcnt vmcnt(0)
	s_and_saveexec_b64 s[4:5], s[38:39]
	s_cbranch_execz .LBB0_231
	s_mov_b64 s[14:15], exec
	v_mbcnt_lo_u32_b32 v141, s14, 0
	v_mbcnt_hi_u32_b32 v141, s15, v141
	v_cmp_eq_u32_e32 vcc, 0, v141
	s_and_b64 s[18:19], exec, vcc
	s_mov_b64 exec, s[18:19]
	s_cbranch_execz .LBB0_231
	s_lshl_b32 s18, s8, 6
	s_ashr_i32 s19, s18, 31
	s_lshl_b64 s[18:19], s[18:19], 2
	s_add_u32 s18, s36, s18
	s_addc_u32 s19, s37, s19
	s_bcnt1_i32_b64 s14, s[14:15]
	v_mov_b32_e32 v141, s14
	global_atomic_add v197, v141, s[18:19]

.LBB0_630:
	s_cmp_lt_i32 s5, 1
	s_cbranch_scc1 .LBB0_670
	s_add_u32 s7, s30, 0x100
	s_addc_u32 s47, s31, 0
	s_mov_b32 s49, 2
	s_mov_b64 s[30:31], 0
	s_add_i32 s34, s49, -2
	s_lshr_b32 s44, s34, 2
	s_lshl_b64 s[36:37], s[44:45], 9
	s_lshr_b32 s44, s49, 2
	s_and_b32 s64, s30, 0x100
	s_lshl_b64 s[34:35], s[44:45], 9
	s_add_u32 s44, s28, s34
	s_addc_u32 s65, s29, s35
	s_add_u32 s34, s30, 0x100
	s_addc_u32 s35, s31, 0
	s_and_b32 s66, s34, 0x100
	s_add_u32 s44, s44, s66
	s_addc_u32 s65, s65, 0
	s_add_u32 s30, s7, s30
	s_addc_u32 s31, s47, s31
	s_add_i32 s66, 0, 0x10000
	s_add_u32 s67, s28, s36
	s_addc_u32 s68, s29, s37
	s_cmp_eq_u32 s5, s49
	s_cselect_b32 s37, s25, s65
	s_cselect_b32 s36, s24, s44
	s_cselect_b32 s31, s27, s31
	s_cselect_b32 s30, s26, s30
	s_add_i32 s44, 0, 0x14000
	v_add_u32_e32 v142, s66, v227
	v_add_u32_e32 v158, s44, v227
	ds_read_b128 v[130:133], v142
	ds_read_b128 v[134:137], v142 offset:1024
	ds_read_b128 v[138:141], v142 offset:2048
	ds_read_b128 v[142:145], v142 offset:3072
	ds_read_b128 v[146:149], v158
	ds_read_b128 v[150:153], v158 offset:1024
	ds_read_b128 v[154:157], v158 offset:2048
	ds_read_b128 v[158:161], v158 offset:3072
	s_add_u32 s64, s67, s64
	s_addc_u32 s65, s68, 0
	s_add_u32 s64, s64, 0x80080
	s_addc_u32 s65, s65, 0
	v_lshl_add_u64 v[194:195], s[64:65], 0, v[198:199]
	s_add_i32 m0, s40, 0xc000
	ds_read_b128 v[162:165], v229
	ds_read_b128 v[166:169], v229 offset:1024
	ds_read_b128 v[170:173], v229 offset:2048
	ds_read_b128 v[174:177], v229 offset:3072
	ds_read_b128 v[178:181], v229 offset:4096
	ds_read_b128 v[182:185], v229 offset:5120
	ds_read_b128 v[186:189], v229 offset:6144
	ds_read_b128 v[190:193], v229 offset:7168
	global_load_lds_dwordx4 v[194:195], off
	v_lshl_add_u64 v[194:195], s[64:65], 0, v[202:203]
	s_add_i32 m0, s40, 0xe000
	s_nop 0
	global_load_lds_dwordx4 v[194:195], off
	s_waitcnt vmcnt(8)
	s_waitcnt lgkmcnt(0)
	s_barrier
	s_setprio 1
	s_waitcnt lgkmcnt(0)
	v_mfma_f32_16x16x32_bf16 v[126:129], v[130:133], v[162:165], 0
	v_mfma_f32_16x16x32_bf16 v[126:129], v[134:137], v[166:169], v[126:129]
	v_mfma_f32_16x16x32_bf16 v[122:125], v[138:141], v[162:165], 0
	v_mfma_f32_16x16x32_bf16 v[122:125], v[142:145], v[166:169], v[122:125]
	v_mfma_f32_16x16x32_bf16 v[110:113], v[130:133], v[170:173], 0
	v_mfma_f32_16x16x32_bf16 v[110:113], v[134:137], v[174:177], v[110:113]
	v_mfma_f32_16x16x32_bf16 v[106:109], v[138:141], v[170:173], 0
	v_mfma_f32_16x16x32_bf16 v[106:109], v[142:145], v[174:177], v[106:109]
	v_mfma_f32_16x16x32_bf16 v[94:97], v[130:133], v[178:181], 0
	v_mfma_f32_16x16x32_bf16 v[94:97], v[134:137], v[182:185], v[94:97]
	v_mfma_f32_16x16x32_bf16 v[90:93], v[138:141], v[178:181], 0
	v_mfma_f32_16x16x32_bf16 v[90:93], v[142:145], v[182:185], v[90:93]
	v_mfma_f32_16x16x32_bf16 v[78:81], v[130:133], v[186:189], 0
	v_mfma_f32_16x16x32_bf16 v[78:81], v[134:137], v[190:193], v[78:81]
	v_mfma_f32_16x16x32_bf16 v[74:77], v[138:141], v[186:189], 0
	v_mfma_f32_16x16x32_bf16 v[74:77], v[142:145], v[190:193], v[74:77]
	s_setprio 0
	s_setprio 1
	v_mfma_f32_16x16x32_bf16 v[118:121], v[146:149], v[162:165], 0
	v_mfma_f32_16x16x32_bf16 v[118:121], v[150:153], v[166:169], v[118:121]
	v_mfma_f32_16x16x32_bf16 v[114:117], v[154:157], v[162:165], 0
	v_mfma_f32_16x16x32_bf16 v[114:117], v[158:161], v[166:169], v[114:117]
	v_mfma_f32_16x16x32_bf16 v[102:105], v[146:149], v[170:173], 0
	v_mfma_f32_16x16x32_bf16 v[102:105], v[150:153], v[174:177], v[102:105]
	v_mfma_f32_16x16x32_bf16 v[98:101], v[154:157], v[170:173], 0
	v_mfma_f32_16x16x32_bf16 v[98:101], v[158:161], v[174:177], v[98:101]
	v_mfma_f32_16x16x32_bf16 v[86:89], v[146:149], v[178:181], 0
	v_mfma_f32_16x16x32_bf16 v[86:89], v[150:153], v[182:185], v[86:89]
	v_mfma_f32_16x16x32_bf16 v[82:85], v[154:157], v[178:181], 0
	v_mfma_f32_16x16x32_bf16 v[82:85], v[158:161], v[182:185], v[82:85]
	v_mfma_f32_16x16x32_bf16 v[70:73], v[146:149], v[186:189], 0
	v_mfma_f32_16x16x32_bf16 v[70:73], v[150:153], v[190:193], v[70:73]
	v_mfma_f32_16x16x32_bf16 v[66:69], v[154:157], v[186:189], 0
	v_mfma_f32_16x16x32_bf16 v[66:69], v[158:161], v[190:193], v[66:69]
	s_setprio 0
	s_barrier
	s_add_i32 s64, s66, s39
	v_lshl_add_u64 v[194:195], s[30:31], 0, v[200:201]
	s_mov_b32 m0, s64
	ds_read_b128 v[162:165], v229 offset:16384
	ds_read_b128 v[166:169], v229 offset:17408
	ds_read_b128 v[170:173], v229 offset:18432
	ds_read_b128 v[174:177], v229 offset:19456
	ds_read_b128 v[178:181], v229 offset:20480
	ds_read_b128 v[182:185], v229 offset:21504
	ds_read_b128 v[186:189], v229 offset:22528
	ds_read_b128 v[190:193], v229 offset:23552
	global_load_lds_dwordx4 v[194:195], off
	s_add_i32 m0, s64, 0x2000
	s_add_u32 s64, s30, 0x80000
	v_lshl_add_u64 v[206:207], s[30:31], 0, v[204:205]
	s_addc_u32 s65, s31, 0
	s_add_i32 s44, s44, s39
	global_load_lds_dwordx4 v[206:207], off
	v_lshl_add_u64 v[208:209], s[64:65], 0, v[200:201]
	s_mov_b32 m0, s44
	v_lshl_add_u64 v[210:211], s[36:37], 0, v[202:203]
	global_load_lds_dwordx4 v[208:209], off
	v_lshl_add_u64 v[208:209], s[64:65], 0, v[204:205]
	s_add_i32 m0, s44, 0x2000
	s_nop 0
	global_load_lds_dwordx4 v[208:209], off
	v_lshl_add_u64 v[208:209], s[36:37], 0, v[198:199]
	s_mov_b32 m0, s40
	s_nop 0
	global_load_lds_dwordx4 v[208:209], off
	s_mov_b32 m0, s41
	s_nop 0
	global_load_lds_dwordx4 v[210:211], off
	s_waitcnt vmcnt(8)
	s_waitcnt lgkmcnt(0)
	s_barrier
	s_setprio 1
	s_waitcnt lgkmcnt(0)
	v_mfma_f32_16x16x32_bf16 v[62:65], v[130:133], v[162:165], 0
	v_mfma_f32_16x16x32_bf16 v[62:65], v[134:137], v[166:169], v[62:65]
	v_mfma_f32_16x16x32_bf16 v[58:61], v[138:141], v[162:165], 0
	v_mfma_f32_16x16x32_bf16 v[58:61], v[142:145], v[166:169], v[58:61]
	v_mfma_f32_16x16x32_bf16 v[46:49], v[130:133], v[170:173], 0
	v_mfma_f32_16x16x32_bf16 v[46:49], v[134:137], v[174:177], v[46:49]
	v_mfma_f32_16x16x32_bf16 v[42:45], v[138:141], v[170:173], 0
	v_mfma_f32_16x16x32_bf16 v[42:45], v[142:145], v[174:177], v[42:45]
	v_mfma_f32_16x16x32_bf16 v[30:33], v[130:133], v[178:181], 0
	v_mfma_f32_16x16x32_bf16 v[30:33], v[134:137], v[182:185], v[30:33]
	v_mfma_f32_16x16x32_bf16 v[26:29], v[138:141], v[178:181], 0
	v_mfma_f32_16x16x32_bf16 v[26:29], v[142:145], v[182:185], v[26:29]
	v_mfma_f32_16x16x32_bf16 v[14:17], v[130:133], v[186:189], 0
	v_mfma_f32_16x16x32_bf16 v[14:17], v[134:137], v[190:193], v[14:17]
	v_mfma_f32_16x16x32_bf16 v[10:13], v[138:141], v[186:189], 0
	v_mfma_f32_16x16x32_bf16 v[10:13], v[142:145], v[190:193], v[10:13]
	s_setprio 0
	s_setprio 1
	v_mfma_f32_16x16x32_bf16 v[54:57], v[146:149], v[162:165], 0
	v_mfma_f32_16x16x32_bf16 v[54:57], v[150:153], v[166:169], v[54:57]
	v_mfma_f32_16x16x32_bf16 v[50:53], v[154:157], v[162:165], 0
	v_mfma_f32_16x16x32_bf16 v[50:53], v[158:161], v[166:169], v[50:53]
	v_mfma_f32_16x16x32_bf16 v[38:41], v[146:149], v[170:173], 0
	v_mfma_f32_16x16x32_bf16 v[38:41], v[150:153], v[174:177], v[38:41]
	v_mfma_f32_16x16x32_bf16 v[34:37], v[154:157], v[170:173], 0
	v_mfma_f32_16x16x32_bf16 v[34:37], v[158:161], v[174:177], v[34:37]
	v_mfma_f32_16x16x32_bf16 v[22:25], v[146:149], v[178:181], 0
	v_mfma_f32_16x16x32_bf16 v[22:25], v[150:153], v[182:185], v[22:25]
	v_mfma_f32_16x16x32_bf16 v[18:21], v[154:157], v[178:181], 0
	v_mfma_f32_16x16x32_bf16 v[18:21], v[158:161], v[182:185], v[18:21]
	v_mfma_f32_16x16x32_bf16 v[6:9], v[146:149], v[186:189], 0
	v_mfma_f32_16x16x32_bf16 v[6:9], v[150:153], v[190:193], v[6:9]
	v_mfma_f32_16x16x32_bf16 v[2:5], v[154:157], v[186:189], 0
	v_mfma_f32_16x16x32_bf16 v[2:5], v[158:161], v[190:193], v[2:5]
	s_setprio 0
	s_barrier
	s_add_i32 s44, 0, 0x18000
	s_add_i32 s64, 0, 0x1c000
	v_add_u32_e32 v142, s44, v227
	v_add_u32_e32 v158, s64, v227
	ds_read_b128 v[130:133], v142
	ds_read_b128 v[134:137], v142 offset:1024
	ds_read_b128 v[138:141], v142 offset:2048
	ds_read_b128 v[142:145], v142 offset:3072
	ds_read_b128 v[146:149], v158
	ds_read_b128 v[150:153], v158 offset:1024
	ds_read_b128 v[154:157], v158 offset:2048
	ds_read_b128 v[158:161], v158 offset:3072
	s_add_u32 s36, s36, 0x80000
	s_addc_u32 s37, s37, 0
	s_mov_b32 m0, s42
	v_lshl_add_u64 v[212:213], s[36:37], 0, v[198:199]
	ds_read_b128 v[162:165], v229 offset:32768
	ds_read_b128 v[166:169], v229 offset:33792
	ds_read_b128 v[170:173], v229 offset:34816
	ds_read_b128 v[174:177], v229 offset:35840
	ds_read_b128 v[178:181], v229 offset:36864
	ds_read_b128 v[182:185], v229 offset:37888
	ds_read_b128 v[186:189], v229 offset:38912
	ds_read_b128 v[190:193], v229 offset:39936
	global_load_lds_dwordx4 v[212:213], off
	v_lshl_add_u64 v[212:213], s[36:37], 0, v[202:203]
	s_mov_b32 m0, s43
	s_nop 0
	global_load_lds_dwordx4 v[212:213], off
	s_waitcnt vmcnt(8)
	s_waitcnt lgkmcnt(0)
	s_barrier
	s_setprio 1
	s_waitcnt lgkmcnt(0)
	v_mfma_f32_16x16x32_bf16 v[126:129], v[130:133], v[162:165], v[126:129]
	v_mfma_f32_16x16x32_bf16 v[126:129], v[134:137], v[166:169], v[126:129]
	v_mfma_f32_16x16x32_bf16 v[122:125], v[138:141], v[162:165], v[122:125]
	v_mfma_f32_16x16x32_bf16 v[122:125], v[142:145], v[166:169], v[122:125]
	v_mfma_f32_16x16x32_bf16 v[110:113], v[130:133], v[170:173], v[110:113]
	v_mfma_f32_16x16x32_bf16 v[110:113], v[134:137], v[174:177], v[110:113]
	v_mfma_f32_16x16x32_bf16 v[106:109], v[138:141], v[170:173], v[106:109]
	v_mfma_f32_16x16x32_bf16 v[106:109], v[142:145], v[174:177], v[106:109]
	v_mfma_f32_16x16x32_bf16 v[94:97], v[130:133], v[178:181], v[94:97]
	v_mfma_f32_16x16x32_bf16 v[94:97], v[134:137], v[182:185], v[94:97]
	v_mfma_f32_16x16x32_bf16 v[90:93], v[138:141], v[178:181], v[90:93]
	v_mfma_f32_16x16x32_bf16 v[90:93], v[142:145], v[182:185], v[90:93]
	v_mfma_f32_16x16x32_bf16 v[78:81], v[130:133], v[186:189], v[78:81]
	v_mfma_f32_16x16x32_bf16 v[78:81], v[134:137], v[190:193], v[78:81]
	v_mfma_f32_16x16x32_bf16 v[74:77], v[138:141], v[186:189], v[74:77]
	v_mfma_f32_16x16x32_bf16 v[74:77], v[142:145], v[190:193], v[74:77]
	s_setprio 0
	s_setprio 1
	v_mfma_f32_16x16x32_bf16 v[118:121], v[146:149], v[162:165], v[118:121]
	v_mfma_f32_16x16x32_bf16 v[118:121], v[150:153], v[166:169], v[118:121]
	v_mfma_f32_16x16x32_bf16 v[114:117], v[154:157], v[162:165], v[114:117]
	v_mfma_f32_16x16x32_bf16 v[114:117], v[158:161], v[166:169], v[114:117]
	v_mfma_f32_16x16x32_bf16 v[102:105], v[146:149], v[170:173], v[102:105]
	v_mfma_f32_16x16x32_bf16 v[102:105], v[150:153], v[174:177], v[102:105]
	v_mfma_f32_16x16x32_bf16 v[98:101], v[154:157], v[170:173], v[98:101]
	v_mfma_f32_16x16x32_bf16 v[98:101], v[158:161], v[174:177], v[98:101]
	v_mfma_f32_16x16x32_bf16 v[86:89], v[146:149], v[178:181], v[86:89]
	v_mfma_f32_16x16x32_bf16 v[86:89], v[150:153], v[182:185], v[86:89]
	v_mfma_f32_16x16x32_bf16 v[82:85], v[154:157], v[178:181], v[82:85]
	v_mfma_f32_16x16x32_bf16 v[82:85], v[158:161], v[182:185], v[82:85]
	v_mfma_f32_16x16x32_bf16 v[70:73], v[146:149], v[186:189], v[70:73]
	v_mfma_f32_16x16x32_bf16 v[70:73], v[150:153], v[190:193], v[70:73]
	v_mfma_f32_16x16x32_bf16 v[66:69], v[154:157], v[186:189], v[66:69]
	v_mfma_f32_16x16x32_bf16 v[66:69], v[158:161], v[190:193], v[66:69]
	s_setprio 0
	s_barrier
	s_add_i32 s36, s44, s39
	v_lshl_add_u64 v[194:195], v[194:195], 0, s[2:3]
	s_mov_b32 m0, s36
	ds_read_b128 v[162:165], v229 offset:49152
	ds_read_b128 v[166:169], v229 offset:50176
	ds_read_b128 v[170:173], v229 offset:51200
	ds_read_b128 v[174:177], v229 offset:52224
	ds_read_b128 v[178:181], v229 offset:53248
	ds_read_b128 v[182:185], v229 offset:54272
	ds_read_b128 v[186:189], v229 offset:55296
	ds_read_b128 v[190:193], v229 offset:56320
	global_load_lds_dwordx4 v[194:195], off
	s_add_i32 m0, s36, 0x2000
	s_add_u32 s30, s30, 0x80080
	v_lshl_add_u64 v[194:195], v[206:207], 0, s[2:3]
	s_addc_u32 s31, s31, 0
	s_add_i32 s36, s64, s39
	global_load_lds_dwordx4 v[194:195], off
	v_lshl_add_u64 v[194:195], s[30:31], 0, v[200:201]
	s_mov_b32 m0, s36
	s_nop 0
	global_load_lds_dwordx4 v[194:195], off
	v_lshl_add_u64 v[194:195], s[30:31], 0, v[204:205]
	s_add_i32 m0, s36, 0x2000
	s_nop 0
	global_load_lds_dwordx4 v[194:195], off
	v_lshl_add_u64 v[194:195], v[208:209], 0, s[2:3]
	s_mov_b32 m0, s50
	s_nop 0
	global_load_lds_dwordx4 v[194:195], off
	v_lshl_add_u64 v[194:195], v[210:211], 0, s[2:3]
	s_mov_b32 m0, s51
	s_nop 0
	global_load_lds_dwordx4 v[194:195], off
	s_waitcnt vmcnt(8)
	s_waitcnt lgkmcnt(0)
	s_barrier
	s_setprio 1
	s_waitcnt lgkmcnt(0)
	v_mfma_f32_16x16x32_bf16 v[62:65], v[130:133], v[162:165], v[62:65]
	v_mfma_f32_16x16x32_bf16 v[62:65], v[134:137], v[166:169], v[62:65]
	v_mfma_f32_16x16x32_bf16 v[58:61], v[138:141], v[162:165], v[58:61]
	v_mfma_f32_16x16x32_bf16 v[58:61], v[142:145], v[166:169], v[58:61]
	v_mfma_f32_16x16x32_bf16 v[46:49], v[130:133], v[170:173], v[46:49]
	v_mfma_f32_16x16x32_bf16 v[46:49], v[134:137], v[174:177], v[46:49]
	v_mfma_f32_16x16x32_bf16 v[42:45], v[138:141], v[170:173], v[42:45]
	v_mfma_f32_16x16x32_bf16 v[42:45], v[142:145], v[174:177], v[42:45]
	v_mfma_f32_16x16x32_bf16 v[30:33], v[130:133], v[178:181], v[30:33]
	v_mfma_f32_16x16x32_bf16 v[30:33], v[134:137], v[182:185], v[30:33]
	v_mfma_f32_16x16x32_bf16 v[26:29], v[138:141], v[178:181], v[26:29]
	v_mfma_f32_16x16x32_bf16 v[26:29], v[142:145], v[182:185], v[26:29]
	v_mfma_f32_16x16x32_bf16 v[14:17], v[130:133], v[186:189], v[14:17]
	v_mfma_f32_16x16x32_bf16 v[14:17], v[134:137], v[190:193], v[14:17]
	v_mfma_f32_16x16x32_bf16 v[10:13], v[138:141], v[186:189], v[10:13]
	v_mfma_f32_16x16x32_bf16 v[10:13], v[142:145], v[190:193], v[10:13]
	s_setprio 0
	s_setprio 1
	v_mfma_f32_16x16x32_bf16 v[54:57], v[146:149], v[162:165], v[54:57]
	v_mfma_f32_16x16x32_bf16 v[54:57], v[150:153], v[166:169], v[54:57]
	v_mfma_f32_16x16x32_bf16 v[50:53], v[154:157], v[162:165], v[50:53]
	v_mfma_f32_16x16x32_bf16 v[50:53], v[158:161], v[166:169], v[50:53]
	v_mfma_f32_16x16x32_bf16 v[38:41], v[146:149], v[170:173], v[38:41]
	v_mfma_f32_16x16x32_bf16 v[38:41], v[150:153], v[174:177], v[38:41]
	v_mfma_f32_16x16x32_bf16 v[34:37], v[154:157], v[170:173], v[34:37]
	v_mfma_f32_16x16x32_bf16 v[34:37], v[158:161], v[174:177], v[34:37]
	v_mfma_f32_16x16x32_bf16 v[22:25], v[146:149], v[178:181], v[22:25]
	v_mfma_f32_16x16x32_bf16 v[22:25], v[150:153], v[182:185], v[22:25]
	v_mfma_f32_16x16x32_bf16 v[18:21], v[154:157], v[178:181], v[18:21]
	v_mfma_f32_16x16x32_bf16 v[18:21], v[158:161], v[182:185], v[18:21]
	v_mfma_f32_16x16x32_bf16 v[6:9], v[146:149], v[186:189], v[6:9]
	v_mfma_f32_16x16x32_bf16 v[6:9], v[150:153], v[190:193], v[6:9]
	v_mfma_f32_16x16x32_bf16 v[2:5], v[154:157], v[186:189], v[2:5]
	v_mfma_f32_16x16x32_bf16 v[2:5], v[158:161], v[190:193], v[2:5]
	s_setprio 0
	s_barrier
	s_add_i32 s36, s49, 2
	s_cmp_ge_i32 s49, s5
	s_mov_b64 s[30:31], s[34:35]
	s_mov_b32 s49, s36
	s_cbranch_scc1 .Lpeel_exit_branch

.Lpeel_exit_branch:
	s_and_b64 vcc, exec, s[14:15]
	s_cbranch_vccz .LBB0_635

.LBB0_782:
	s_add_u32 s58, s34, 0x100
	s_addc_u32 s59, s35, 0
	s_mov_b32 s60, 2
	s_mov_b64 s[34:35], 0
	s_add_i32 s36, s60, -2
	s_lshr_b32 s44, s36, 2
	s_lshl_b64 s[38:39], s[44:45], 9
	s_lshr_b32 s44, s60, 2
	s_and_b32 s61, s34, 0x100
	s_lshl_b64 s[36:37], s[44:45], 9
	s_add_u32 s44, s30, s36
	s_addc_u32 s62, s31, s37
	s_add_u32 s36, s34, 0x100
	s_addc_u32 s37, s35, 0
	s_and_b32 s63, s36, 0x100
	s_add_u32 s44, s44, s63
	s_addc_u32 s62, s62, 0
	s_add_u32 s34, s58, s34
	s_addc_u32 s35, s59, s35
	s_add_i32 s64, 0, 0x10000
	s_add_u32 s63, s30, s38
	s_addc_u32 s65, s31, s39
	s_cmp_eq_u32 s57, s60
	s_cselect_b32 s39, s27, s62
	s_cselect_b32 s38, s26, s44
	s_cselect_b32 s35, s29, s35
	s_cselect_b32 s34, s28, s34
	s_add_i32 s44, 0, 0x14000
	v_add_u32_e32 v152, s64, v137
	v_add_u32_e32 v168, s44, v137
	ds_read_b128 v[140:143], v152
	ds_read_b128 v[144:147], v152 offset:1024
	ds_read_b128 v[148:151], v152 offset:2048
	ds_read_b128 v[152:155], v152 offset:3072
	ds_read_b128 v[156:159], v168
	ds_read_b128 v[160:163], v168 offset:1024
	ds_read_b128 v[164:167], v168 offset:2048
	ds_read_b128 v[168:171], v168 offset:3072
	s_add_u32 s61, s63, s61
	s_addc_u32 s63, s65, 0
	s_add_u32 s62, s61, 0x80080
	s_addc_u32 s63, s63, 0
	v_lshl_add_u64 v[206:207], s[62:63], 0, v[130:131]
	s_add_i32 m0, s11, 0xc000
	ds_read_b128 v[172:175], v139
	ds_read_b128 v[176:179], v139 offset:1024
	ds_read_b128 v[180:183], v139 offset:2048
	ds_read_b128 v[184:187], v139 offset:3072
	ds_read_b128 v[188:191], v139 offset:4096
	ds_read_b128 v[192:195], v139 offset:5120
	ds_read_b128 v[198:201], v139 offset:6144
	ds_read_b128 v[202:205], v139 offset:7168
	global_load_lds_dwordx4 v[206:207], off
	v_lshl_add_u64 v[206:207], s[62:63], 0, v[132:133]
	s_add_i32 m0, s11, 0xe000
	s_nop 0
	global_load_lds_dwordx4 v[206:207], off
	s_waitcnt vmcnt(8)
	s_waitcnt lgkmcnt(0)
	s_barrier
	s_setprio 1
	s_waitcnt lgkmcnt(0)
	v_mfma_f32_16x16x32_bf16 v[126:129], v[140:143], v[172:175], 0
	v_mfma_f32_16x16x32_bf16 v[126:129], v[144:147], v[176:179], v[126:129]
	v_mfma_f32_16x16x32_bf16 v[122:125], v[148:151], v[172:175], 0
	v_mfma_f32_16x16x32_bf16 v[122:125], v[152:155], v[176:179], v[122:125]
	v_mfma_f32_16x16x32_bf16 v[110:113], v[140:143], v[180:183], 0
	v_mfma_f32_16x16x32_bf16 v[110:113], v[144:147], v[184:187], v[110:113]
	v_mfma_f32_16x16x32_bf16 v[106:109], v[148:151], v[180:183], 0
	v_mfma_f32_16x16x32_bf16 v[106:109], v[152:155], v[184:187], v[106:109]
	v_mfma_f32_16x16x32_bf16 v[94:97], v[140:143], v[188:191], 0
	v_mfma_f32_16x16x32_bf16 v[94:97], v[144:147], v[192:195], v[94:97]
	v_mfma_f32_16x16x32_bf16 v[90:93], v[148:151], v[188:191], 0
	v_mfma_f32_16x16x32_bf16 v[90:93], v[152:155], v[192:195], v[90:93]
	v_mfma_f32_16x16x32_bf16 v[78:81], v[140:143], v[198:201], 0
	v_mfma_f32_16x16x32_bf16 v[78:81], v[144:147], v[202:205], v[78:81]
	v_mfma_f32_16x16x32_bf16 v[74:77], v[148:151], v[198:201], 0
	v_mfma_f32_16x16x32_bf16 v[74:77], v[152:155], v[202:205], v[74:77]
	s_setprio 0
	s_setprio 1
	v_mfma_f32_16x16x32_bf16 v[118:121], v[156:159], v[172:175], 0
	v_mfma_f32_16x16x32_bf16 v[118:121], v[160:163], v[176:179], v[118:121]
	v_mfma_f32_16x16x32_bf16 v[114:117], v[164:167], v[172:175], 0
	v_mfma_f32_16x16x32_bf16 v[114:117], v[168:171], v[176:179], v[114:117]
	v_mfma_f32_16x16x32_bf16 v[102:105], v[156:159], v[180:183], 0
	v_mfma_f32_16x16x32_bf16 v[102:105], v[160:163], v[184:187], v[102:105]
	v_mfma_f32_16x16x32_bf16 v[98:101], v[164:167], v[180:183], 0
	v_mfma_f32_16x16x32_bf16 v[98:101], v[168:171], v[184:187], v[98:101]
	v_mfma_f32_16x16x32_bf16 v[86:89], v[156:159], v[188:191], 0
	v_mfma_f32_16x16x32_bf16 v[86:89], v[160:163], v[192:195], v[86:89]
	v_mfma_f32_16x16x32_bf16 v[82:85], v[164:167], v[188:191], 0
	v_mfma_f32_16x16x32_bf16 v[82:85], v[168:171], v[192:195], v[82:85]
	v_mfma_f32_16x16x32_bf16 v[70:73], v[156:159], v[198:201], 0
	v_mfma_f32_16x16x32_bf16 v[70:73], v[160:163], v[202:205], v[70:73]
	v_mfma_f32_16x16x32_bf16 v[66:69], v[164:167], v[198:201], 0
	v_mfma_f32_16x16x32_bf16 v[66:69], v[168:171], v[202:205], v[66:69]
	s_setprio 0
	s_barrier
	s_add_i32 s61, s64, s9
	v_lshl_add_u64 v[206:207], s[34:35], 0, v[196:197]
	s_mov_b32 m0, s61
	ds_read_b128 v[172:175], v139 offset:16384
	ds_read_b128 v[176:179], v139 offset:17408
	ds_read_b128 v[180:183], v139 offset:18432
	ds_read_b128 v[184:187], v139 offset:19456
	ds_read_b128 v[188:191], v139 offset:20480
	ds_read_b128 v[192:195], v139 offset:21504
	ds_read_b128 v[198:201], v139 offset:22528
	ds_read_b128 v[202:205], v139 offset:23552
	global_load_lds_dwordx4 v[206:207], off
	s_add_i32 m0, s61, 0x2000
	s_add_u32 s62, s34, 0x80000
	v_lshl_add_u64 v[208:209], s[34:35], 0, v[134:135]
	s_addc_u32 s63, s35, 0
	s_add_i32 s44, s44, s9
	global_load_lds_dwordx4 v[208:209], off
	v_lshl_add_u64 v[210:211], s[62:63], 0, v[196:197]
	s_mov_b32 m0, s44
	v_lshl_add_u64 v[212:213], s[38:39], 0, v[132:133]
	global_load_lds_dwordx4 v[210:211], off
	v_lshl_add_u64 v[210:211], s[62:63], 0, v[134:135]
	s_add_i32 m0, s44, 0x2000
	s_nop 0
	global_load_lds_dwordx4 v[210:211], off
	v_lshl_add_u64 v[210:211], s[38:39], 0, v[130:131]
	s_mov_b32 m0, s11
	s_nop 0
	global_load_lds_dwordx4 v[210:211], off
	s_mov_b32 m0, s33
	s_nop 0
	global_load_lds_dwordx4 v[212:213], off
	s_waitcnt vmcnt(8)
	s_waitcnt lgkmcnt(0)
	s_barrier
	s_setprio 1
	s_waitcnt lgkmcnt(0)
	v_mfma_f32_16x16x32_bf16 v[62:65], v[140:143], v[172:175], 0
	v_mfma_f32_16x16x32_bf16 v[62:65], v[144:147], v[176:179], v[62:65]
	v_mfma_f32_16x16x32_bf16 v[58:61], v[148:151], v[172:175], 0
	v_mfma_f32_16x16x32_bf16 v[58:61], v[152:155], v[176:179], v[58:61]
	v_mfma_f32_16x16x32_bf16 v[46:49], v[140:143], v[180:183], 0
	v_mfma_f32_16x16x32_bf16 v[46:49], v[144:147], v[184:187], v[46:49]
	v_mfma_f32_16x16x32_bf16 v[42:45], v[148:151], v[180:183], 0
	v_mfma_f32_16x16x32_bf16 v[42:45], v[152:155], v[184:187], v[42:45]
	v_mfma_f32_16x16x32_bf16 v[30:33], v[140:143], v[188:191], 0
	v_mfma_f32_16x16x32_bf16 v[30:33], v[144:147], v[192:195], v[30:33]
	v_mfma_f32_16x16x32_bf16 v[26:29], v[148:151], v[188:191], 0
	v_mfma_f32_16x16x32_bf16 v[26:29], v[152:155], v[192:195], v[26:29]
	v_mfma_f32_16x16x32_bf16 v[14:17], v[140:143], v[198:201], 0
	v_mfma_f32_16x16x32_bf16 v[14:17], v[144:147], v[202:205], v[14:17]
	v_mfma_f32_16x16x32_bf16 v[10:13], v[148:151], v[198:201], 0
	v_mfma_f32_16x16x32_bf16 v[10:13], v[152:155], v[202:205], v[10:13]
	s_setprio 0
	s_setprio 1
	v_mfma_f32_16x16x32_bf16 v[54:57], v[156:159], v[172:175], 0
	v_mfma_f32_16x16x32_bf16 v[54:57], v[160:163], v[176:179], v[54:57]
	v_mfma_f32_16x16x32_bf16 v[50:53], v[164:167], v[172:175], 0
	v_mfma_f32_16x16x32_bf16 v[50:53], v[168:171], v[176:179], v[50:53]
	v_mfma_f32_16x16x32_bf16 v[38:41], v[156:159], v[180:183], 0
	v_mfma_f32_16x16x32_bf16 v[38:41], v[160:163], v[184:187], v[38:41]
	v_mfma_f32_16x16x32_bf16 v[34:37], v[164:167], v[180:183], 0
	v_mfma_f32_16x16x32_bf16 v[34:37], v[168:171], v[184:187], v[34:37]
	v_mfma_f32_16x16x32_bf16 v[22:25], v[156:159], v[188:191], 0
	v_mfma_f32_16x16x32_bf16 v[22:25], v[160:163], v[192:195], v[22:25]
	v_mfma_f32_16x16x32_bf16 v[18:21], v[164:167], v[188:191], 0
	v_mfma_f32_16x16x32_bf16 v[18:21], v[168:171], v[192:195], v[18:21]
	v_mfma_f32_16x16x32_bf16 v[6:9], v[156:159], v[198:201], 0
	v_mfma_f32_16x16x32_bf16 v[6:9], v[160:163], v[202:205], v[6:9]
	v_mfma_f32_16x16x32_bf16 v[2:5], v[164:167], v[198:201], 0
	v_mfma_f32_16x16x32_bf16 v[2:5], v[168:171], v[202:205], v[2:5]
	s_setprio 0
	s_barrier
	s_add_i32 s44, 0, 0x18000
	s_add_i32 s61, 0, 0x1c000
	v_add_u32_e32 v152, s44, v137
	v_add_u32_e32 v168, s61, v137
	ds_read_b128 v[140:143], v152
	ds_read_b128 v[144:147], v152 offset:1024
	ds_read_b128 v[148:151], v152 offset:2048
	ds_read_b128 v[152:155], v152 offset:3072
	ds_read_b128 v[156:159], v168
	ds_read_b128 v[160:163], v168 offset:1024
	ds_read_b128 v[164:167], v168 offset:2048
	ds_read_b128 v[168:171], v168 offset:3072
	s_add_u32 s38, s38, 0x80000
	s_addc_u32 s39, s39, 0
	s_mov_b32 m0, s40
	v_lshl_add_u64 v[214:215], s[38:39], 0, v[130:131]
	ds_read_b128 v[172:175], v139 offset:32768
	ds_read_b128 v[176:179], v139 offset:33792
	ds_read_b128 v[180:183], v139 offset:34816
	ds_read_b128 v[184:187], v139 offset:35840
	ds_read_b128 v[188:191], v139 offset:36864
	ds_read_b128 v[192:195], v139 offset:37888
	ds_read_b128 v[198:201], v139 offset:38912
	ds_read_b128 v[202:205], v139 offset:39936
	global_load_lds_dwordx4 v[214:215], off
	v_lshl_add_u64 v[214:215], s[38:39], 0, v[132:133]
	s_mov_b32 m0, s41
	s_nop 0
	global_load_lds_dwordx4 v[214:215], off
	s_waitcnt vmcnt(8)
	s_waitcnt lgkmcnt(0)
	s_barrier
	s_setprio 1
	s_waitcnt lgkmcnt(0)
	v_mfma_f32_16x16x32_bf16 v[126:129], v[140:143], v[172:175], v[126:129]
	v_mfma_f32_16x16x32_bf16 v[126:129], v[144:147], v[176:179], v[126:129]
	v_mfma_f32_16x16x32_bf16 v[122:125], v[148:151], v[172:175], v[122:125]
	v_mfma_f32_16x16x32_bf16 v[122:125], v[152:155], v[176:179], v[122:125]
	v_mfma_f32_16x16x32_bf16 v[110:113], v[140:143], v[180:183], v[110:113]
	v_mfma_f32_16x16x32_bf16 v[110:113], v[144:147], v[184:187], v[110:113]
	v_mfma_f32_16x16x32_bf16 v[106:109], v[148:151], v[180:183], v[106:109]
	v_mfma_f32_16x16x32_bf16 v[106:109], v[152:155], v[184:187], v[106:109]
	v_mfma_f32_16x16x32_bf16 v[94:97], v[140:143], v[188:191], v[94:97]
	v_mfma_f32_16x16x32_bf16 v[94:97], v[144:147], v[192:195], v[94:97]
	v_mfma_f32_16x16x32_bf16 v[90:93], v[148:151], v[188:191], v[90:93]
	v_mfma_f32_16x16x32_bf16 v[90:93], v[152:155], v[192:195], v[90:93]
	v_mfma_f32_16x16x32_bf16 v[78:81], v[140:143], v[198:201], v[78:81]
	v_mfma_f32_16x16x32_bf16 v[78:81], v[144:147], v[202:205], v[78:81]
	v_mfma_f32_16x16x32_bf16 v[74:77], v[148:151], v[198:201], v[74:77]
	v_mfma_f32_16x16x32_bf16 v[74:77], v[152:155], v[202:205], v[74:77]
	s_setprio 0
	s_setprio 1
	v_mfma_f32_16x16x32_bf16 v[118:121], v[156:159], v[172:175], v[118:121]
	v_mfma_f32_16x16x32_bf16 v[118:121], v[160:163], v[176:179], v[118:121]
	v_mfma_f32_16x16x32_bf16 v[114:117], v[164:167], v[172:175], v[114:117]
	v_mfma_f32_16x16x32_bf16 v[114:117], v[168:171], v[176:179], v[114:117]
	v_mfma_f32_16x16x32_bf16 v[102:105], v[156:159], v[180:183], v[102:105]
	v_mfma_f32_16x16x32_bf16 v[102:105], v[160:163], v[184:187], v[102:105]
	v_mfma_f32_16x16x32_bf16 v[98:101], v[164:167], v[180:183], v[98:101]
	v_mfma_f32_16x16x32_bf16 v[98:101], v[168:171], v[184:187], v[98:101]
	v_mfma_f32_16x16x32_bf16 v[86:89], v[156:159], v[188:191], v[86:89]
	v_mfma_f32_16x16x32_bf16 v[86:89], v[160:163], v[192:195], v[86:89]
	v_mfma_f32_16x16x32_bf16 v[82:85], v[164:167], v[188:191], v[82:85]
	v_mfma_f32_16x16x32_bf16 v[82:85], v[168:171], v[192:195], v[82:85]
	v_mfma_f32_16x16x32_bf16 v[70:73], v[156:159], v[198:201], v[70:73]
	v_mfma_f32_16x16x32_bf16 v[70:73], v[160:163], v[202:205], v[70:73]
	v_mfma_f32_16x16x32_bf16 v[66:69], v[164:167], v[198:201], v[66:69]
	v_mfma_f32_16x16x32_bf16 v[66:69], v[168:171], v[202:205], v[66:69]
	s_setprio 0
	s_barrier
	s_add_i32 s38, s44, s9
	v_lshl_add_u64 v[206:207], v[206:207], 0, s[2:3]
	s_mov_b32 m0, s38
	ds_read_b128 v[172:175], v139 offset:49152
	ds_read_b128 v[176:179], v139 offset:50176
	ds_read_b128 v[180:183], v139 offset:51200
	ds_read_b128 v[184:187], v139 offset:52224
	ds_read_b128 v[188:191], v139 offset:53248
	ds_read_b128 v[192:195], v139 offset:54272
	ds_read_b128 v[198:201], v139 offset:55296
	ds_read_b128 v[202:205], v139 offset:56320
	global_load_lds_dwordx4 v[206:207], off
	s_add_i32 m0, s38, 0x2000
	s_add_u32 s34, s34, 0x80080
	v_lshl_add_u64 v[206:207], v[208:209], 0, s[2:3]
	s_addc_u32 s35, s35, 0
	s_add_i32 s38, s61, s9
	global_load_lds_dwordx4 v[206:207], off
	v_lshl_add_u64 v[206:207], s[34:35], 0, v[196:197]
	s_mov_b32 m0, s38
	s_nop 0
	global_load_lds_dwordx4 v[206:207], off
	v_lshl_add_u64 v[206:207], s[34:35], 0, v[134:135]
	s_add_i32 m0, s38, 0x2000
	s_nop 0
	global_load_lds_dwordx4 v[206:207], off
	v_lshl_add_u64 v[206:207], v[210:211], 0, s[2:3]
	s_mov_b32 m0, s50
	s_nop 0
	global_load_lds_dwordx4 v[206:207], off
	v_lshl_add_u64 v[206:207], v[212:213], 0, s[2:3]
	s_mov_b32 m0, s51
	s_nop 0
	global_load_lds_dwordx4 v[206:207], off
	s_waitcnt vmcnt(8)
	s_waitcnt lgkmcnt(0)
	s_barrier
	s_setprio 1
	s_waitcnt lgkmcnt(0)
	v_mfma_f32_16x16x32_bf16 v[62:65], v[140:143], v[172:175], v[62:65]
	v_mfma_f32_16x16x32_bf16 v[62:65], v[144:147], v[176:179], v[62:65]
	v_mfma_f32_16x16x32_bf16 v[58:61], v[148:151], v[172:175], v[58:61]
	v_mfma_f32_16x16x32_bf16 v[58:61], v[152:155], v[176:179], v[58:61]
	v_mfma_f32_16x16x32_bf16 v[46:49], v[140:143], v[180:183], v[46:49]
	v_mfma_f32_16x16x32_bf16 v[46:49], v[144:147], v[184:187], v[46:49]
	v_mfma_f32_16x16x32_bf16 v[42:45], v[148:151], v[180:183], v[42:45]
	v_mfma_f32_16x16x32_bf16 v[42:45], v[152:155], v[184:187], v[42:45]
	v_mfma_f32_16x16x32_bf16 v[30:33], v[140:143], v[188:191], v[30:33]
	v_mfma_f32_16x16x32_bf16 v[30:33], v[144:147], v[192:195], v[30:33]
	v_mfma_f32_16x16x32_bf16 v[26:29], v[148:151], v[188:191], v[26:29]
	v_mfma_f32_16x16x32_bf16 v[26:29], v[152:155], v[192:195], v[26:29]
	v_mfma_f32_16x16x32_bf16 v[14:17], v[140:143], v[198:201], v[14:17]
	v_mfma_f32_16x16x32_bf16 v[14:17], v[144:147], v[202:205], v[14:17]
	v_mfma_f32_16x16x32_bf16 v[10:13], v[148:151], v[198:201], v[10:13]
	v_mfma_f32_16x16x32_bf16 v[10:13], v[152:155], v[202:205], v[10:13]
	s_setprio 0
	s_setprio 1
	v_mfma_f32_16x16x32_bf16 v[54:57], v[156:159], v[172:175], v[54:57]
	v_mfma_f32_16x16x32_bf16 v[54:57], v[160:163], v[176:179], v[54:57]
	v_mfma_f32_16x16x32_bf16 v[50:53], v[164:167], v[172:175], v[50:53]
	v_mfma_f32_16x16x32_bf16 v[50:53], v[168:171], v[176:179], v[50:53]
	v_mfma_f32_16x16x32_bf16 v[38:41], v[156:159], v[180:183], v[38:41]
	v_mfma_f32_16x16x32_bf16 v[38:41], v[160:163], v[184:187], v[38:41]
	v_mfma_f32_16x16x32_bf16 v[34:37], v[164:167], v[180:183], v[34:37]
	v_mfma_f32_16x16x32_bf16 v[34:37], v[168:171], v[184:187], v[34:37]
	v_mfma_f32_16x16x32_bf16 v[22:25], v[156:159], v[188:191], v[22:25]
	v_mfma_f32_16x16x32_bf16 v[22:25], v[160:163], v[192:195], v[22:25]
	v_mfma_f32_16x16x32_bf16 v[18:21], v[164:167], v[188:191], v[18:21]
	v_mfma_f32_16x16x32_bf16 v[18:21], v[168:171], v[192:195], v[18:21]
	v_mfma_f32_16x16x32_bf16 v[6:9], v[156:159], v[198:201], v[6:9]
	v_mfma_f32_16x16x32_bf16 v[6:9], v[160:163], v[202:205], v[6:9]
	v_mfma_f32_16x16x32_bf16 v[2:5], v[164:167], v[198:201], v[2:5]
	v_mfma_f32_16x16x32_bf16 v[2:5], v[168:171], v[202:205], v[2:5]
	s_setprio 0
	s_barrier
	s_add_i32 s38, s60, 2
	s_cmp_ge_i32 s60, s57
	s_mov_b64 s[34:35], s[36:37]
	s_mov_b32 s60, s38
	s_cbranch_scc1 .Lpeel_exit_wout

.Lpeel_exit_wout:
	v_readlane_b32 s58, v254, 51
	v_readlane_b32 s59, v254, 52
	s_and_b64 vcc, exec, s[12:13]
	s_cbranch_vccz .LBB0_786

.LBB0_962:
	s_add_u32 s1, s18, 0x100
	s_addc_u32 s7, s19, 0
	s_mov_b32 s22, -2
	s_mov_b64 s[18:19], 0
	s_add_i32 s43, s22, 2
	s_lshr_b32 s44, s43, 2
	s_add_i32 s20, s22, 4
	s_lshl_b64 s[50:51], s[44:45], 9
	s_lshr_b32 s44, s20, 2
	s_and_b32 s47, s18, 0x100
	s_lshl_b64 s[20:21], s[44:45], 9
	s_add_u32 s23, s12, s20
	s_addc_u32 s44, s13, s21
	s_add_u32 s20, s18, 0x100
	s_addc_u32 s21, s19, 0
	s_and_b32 s49, s20, 0x100
	s_add_u32 s49, s23, s49
	s_addc_u32 s23, s44, 0
	s_add_u32 s18, s1, s18
	s_addc_u32 s19, s7, s19
	s_add_i32 s44, 0, 0x10000
	s_add_u32 s50, s12, s50
	s_addc_u32 s51, s13, s51
	s_cmp_eq_u32 s22, 28
	s_cselect_b32 s23, s15, s23
	s_cselect_b32 s22, s14, s49
	v_add_u32_e32 v138, s44, v140
	s_cselect_b32 s19, s17, s19
	s_cselect_b32 s18, s16, s18
	s_add_i32 s49, 0, 0x14000
	ds_read_b128 v[142:145], v138
	ds_read_b128 v[146:149], v138 offset:1024
	ds_read_b128 v[150:153], v138 offset:2048
	ds_read_b128 v[154:157], v138 offset:3072
	v_add_u32_e32 v138, s49, v140
	ds_read_b128 v[158:161], v138
	ds_read_b128 v[162:165], v138 offset:1024
	ds_read_b128 v[166:169], v138 offset:2048
	ds_read_b128 v[170:173], v138 offset:3072
	s_add_u32 s47, s50, s47
	s_addc_u32 s51, s51, 0
	s_add_u32 s50, s47, 0x80080
	s_addc_u32 s51, s51, 0
	v_lshl_add_u64 v[138:139], s[50:51], 0, v[134:135]
	s_add_i32 m0, s33, 0xc000
	ds_read_b128 v[174:177], v141
	ds_read_b128 v[178:181], v141 offset:1024
	ds_read_b128 v[182:185], v141 offset:2048
	ds_read_b128 v[186:189], v141 offset:3072
	ds_read_b128 v[190:193], v141 offset:4096
	ds_read_b128 v[198:201], v141 offset:5120
	ds_read_b128 v[202:205], v141 offset:6144
	ds_read_b128 v[206:209], v141 offset:7168
	global_load_lds_dwordx4 v[138:139], off
	v_lshl_add_u64 v[138:139], s[50:51], 0, v[132:133]
	s_add_i32 m0, s33, 0xe000
	s_nop 0
	global_load_lds_dwordx4 v[138:139], off
	s_waitcnt vmcnt(8)
	s_waitcnt lgkmcnt(0)
	s_barrier
	s_setprio 1
	s_waitcnt lgkmcnt(0)
	v_mfma_f32_16x16x32_bf16 v[126:129], v[142:145], v[174:177], 0
	v_mfma_f32_16x16x32_bf16 v[126:129], v[146:149], v[178:181], v[126:129]
	v_mfma_f32_16x16x32_bf16 v[122:125], v[150:153], v[174:177], 0
	v_mfma_f32_16x16x32_bf16 v[122:125], v[154:157], v[178:181], v[122:125]
	v_mfma_f32_16x16x32_bf16 v[110:113], v[142:145], v[182:185], 0
	v_mfma_f32_16x16x32_bf16 v[110:113], v[146:149], v[186:189], v[110:113]
	v_mfma_f32_16x16x32_bf16 v[106:109], v[150:153], v[182:185], 0
	v_mfma_f32_16x16x32_bf16 v[106:109], v[154:157], v[186:189], v[106:109]
	v_mfma_f32_16x16x32_bf16 v[94:97], v[142:145], v[190:193], 0
	v_mfma_f32_16x16x32_bf16 v[94:97], v[146:149], v[198:201], v[94:97]
	v_mfma_f32_16x16x32_bf16 v[90:93], v[150:153], v[190:193], 0
	v_mfma_f32_16x16x32_bf16 v[90:93], v[154:157], v[198:201], v[90:93]
	v_mfma_f32_16x16x32_bf16 v[78:81], v[142:145], v[202:205], 0
	v_mfma_f32_16x16x32_bf16 v[78:81], v[146:149], v[206:209], v[78:81]
	v_mfma_f32_16x16x32_bf16 v[74:77], v[150:153], v[202:205], 0
	v_mfma_f32_16x16x32_bf16 v[74:77], v[154:157], v[206:209], v[74:77]
	s_setprio 0
	s_setprio 1
	v_mfma_f32_16x16x32_bf16 v[118:121], v[158:161], v[174:177], 0
	v_mfma_f32_16x16x32_bf16 v[118:121], v[162:165], v[178:181], v[118:121]
	v_mfma_f32_16x16x32_bf16 v[114:117], v[166:169], v[174:177], 0
	v_mfma_f32_16x16x32_bf16 v[114:117], v[170:173], v[178:181], v[114:117]
	v_mfma_f32_16x16x32_bf16 v[102:105], v[158:161], v[182:185], 0
	v_mfma_f32_16x16x32_bf16 v[102:105], v[162:165], v[186:189], v[102:105]
	v_mfma_f32_16x16x32_bf16 v[98:101], v[166:169], v[182:185], 0
	v_mfma_f32_16x16x32_bf16 v[98:101], v[170:173], v[186:189], v[98:101]
	v_mfma_f32_16x16x32_bf16 v[86:89], v[158:161], v[190:193], 0
	v_mfma_f32_16x16x32_bf16 v[86:89], v[162:165], v[198:201], v[86:89]
	v_mfma_f32_16x16x32_bf16 v[82:85], v[166:169], v[190:193], 0
	v_mfma_f32_16x16x32_bf16 v[82:85], v[170:173], v[198:201], v[82:85]
	v_mfma_f32_16x16x32_bf16 v[70:73], v[158:161], v[202:205], 0
	v_mfma_f32_16x16x32_bf16 v[70:73], v[162:165], v[206:209], v[70:73]
	v_mfma_f32_16x16x32_bf16 v[66:69], v[166:169], v[202:205], 0
	v_mfma_f32_16x16x32_bf16 v[66:69], v[170:173], v[206:209], v[66:69]
	s_setprio 0
	s_barrier
	s_add_i32 s44, s44, s31
	v_lshl_add_u64 v[138:139], s[18:19], 0, v[196:197]
	s_mov_b32 m0, s44
	ds_read_b128 v[174:177], v141 offset:16384
	ds_read_b128 v[178:181], v141 offset:17408
	ds_read_b128 v[182:185], v141 offset:18432
	ds_read_b128 v[186:189], v141 offset:19456
	ds_read_b128 v[190:193], v141 offset:20480
	ds_read_b128 v[198:201], v141 offset:21504
	ds_read_b128 v[202:205], v141 offset:22528
	ds_read_b128 v[206:209], v141 offset:23552
	global_load_lds_dwordx4 v[138:139], off
	s_add_i32 m0, s44, 0x2000
	s_add_u32 s50, s18, 0x80000
	v_lshl_add_u64 v[194:195], s[18:19], 0, v[130:131]
	s_addc_u32 s51, s19, 0
	s_add_i32 s44, s49, s31
	global_load_lds_dwordx4 v[194:195], off
	v_lshl_add_u64 v[210:211], s[50:51], 0, v[196:197]
	s_mov_b32 m0, s44
	v_lshl_add_u64 v[212:213], s[22:23], 0, v[132:133]
	global_load_lds_dwordx4 v[210:211], off
	v_lshl_add_u64 v[210:211], s[50:51], 0, v[130:131]
	s_add_i32 m0, s44, 0x2000
	s_nop 0
	global_load_lds_dwordx4 v[210:211], off
	v_lshl_add_u64 v[210:211], s[22:23], 0, v[134:135]
	s_mov_b32 m0, s33
	s_nop 0
	global_load_lds_dwordx4 v[210:211], off
	s_mov_b32 m0, s34
	s_nop 0
	global_load_lds_dwordx4 v[212:213], off
	s_waitcnt vmcnt(8)
	s_waitcnt lgkmcnt(0)
	s_barrier
	s_setprio 1
	s_waitcnt lgkmcnt(0)
	v_mfma_f32_16x16x32_bf16 v[62:65], v[142:145], v[174:177], 0
	v_mfma_f32_16x16x32_bf16 v[62:65], v[146:149], v[178:181], v[62:65]
	v_mfma_f32_16x16x32_bf16 v[58:61], v[150:153], v[174:177], 0
	v_mfma_f32_16x16x32_bf16 v[58:61], v[154:157], v[178:181], v[58:61]
	v_mfma_f32_16x16x32_bf16 v[46:49], v[142:145], v[182:185], 0
	v_mfma_f32_16x16x32_bf16 v[46:49], v[146:149], v[186:189], v[46:49]
	v_mfma_f32_16x16x32_bf16 v[42:45], v[150:153], v[182:185], 0
	v_mfma_f32_16x16x32_bf16 v[42:45], v[154:157], v[186:189], v[42:45]
	v_mfma_f32_16x16x32_bf16 v[30:33], v[142:145], v[190:193], 0
	v_mfma_f32_16x16x32_bf16 v[30:33], v[146:149], v[198:201], v[30:33]
	v_mfma_f32_16x16x32_bf16 v[26:29], v[150:153], v[190:193], 0
	v_mfma_f32_16x16x32_bf16 v[26:29], v[154:157], v[198:201], v[26:29]
	v_mfma_f32_16x16x32_bf16 v[14:17], v[142:145], v[202:205], 0
	v_mfma_f32_16x16x32_bf16 v[14:17], v[146:149], v[206:209], v[14:17]
	v_mfma_f32_16x16x32_bf16 v[10:13], v[150:153], v[202:205], 0
	v_mfma_f32_16x16x32_bf16 v[10:13], v[154:157], v[206:209], v[10:13]
	s_setprio 0
	s_setprio 1
	v_mfma_f32_16x16x32_bf16 v[54:57], v[158:161], v[174:177], 0
	v_mfma_f32_16x16x32_bf16 v[54:57], v[162:165], v[178:181], v[54:57]
	v_mfma_f32_16x16x32_bf16 v[50:53], v[166:169], v[174:177], 0
	v_mfma_f32_16x16x32_bf16 v[50:53], v[170:173], v[178:181], v[50:53]
	v_mfma_f32_16x16x32_bf16 v[38:41], v[158:161], v[182:185], 0
	v_mfma_f32_16x16x32_bf16 v[38:41], v[162:165], v[186:189], v[38:41]
	v_mfma_f32_16x16x32_bf16 v[34:37], v[166:169], v[182:185], 0
	v_mfma_f32_16x16x32_bf16 v[34:37], v[170:173], v[186:189], v[34:37]
	v_mfma_f32_16x16x32_bf16 v[22:25], v[158:161], v[190:193], 0
	v_mfma_f32_16x16x32_bf16 v[22:25], v[162:165], v[198:201], v[22:25]
	v_mfma_f32_16x16x32_bf16 v[18:21], v[166:169], v[190:193], 0
	v_mfma_f32_16x16x32_bf16 v[18:21], v[170:173], v[198:201], v[18:21]
	v_mfma_f32_16x16x32_bf16 v[6:9], v[158:161], v[202:205], 0
	v_mfma_f32_16x16x32_bf16 v[6:9], v[162:165], v[206:209], v[6:9]
	v_mfma_f32_16x16x32_bf16 v[2:5], v[166:169], v[202:205], 0
	v_mfma_f32_16x16x32_bf16 v[2:5], v[170:173], v[206:209], v[2:5]
	s_setprio 0
	s_barrier
	s_add_i32 s44, 0, 0x18000
	s_add_i32 s47, 0, 0x1c000
	v_add_u32_e32 v154, s44, v140
	v_add_u32_e32 v170, s47, v140
	ds_read_b128 v[142:145], v154
	ds_read_b128 v[146:149], v154 offset:1024
	ds_read_b128 v[150:153], v154 offset:2048
	ds_read_b128 v[154:157], v154 offset:3072
	ds_read_b128 v[158:161], v170
	ds_read_b128 v[162:165], v170 offset:1024
	ds_read_b128 v[166:169], v170 offset:2048
	ds_read_b128 v[170:173], v170 offset:3072
	s_add_u32 s22, s22, 0x80000
	s_addc_u32 s23, s23, 0
	s_mov_b32 m0, s35
	v_lshl_add_u64 v[214:215], s[22:23], 0, v[134:135]
	ds_read_b128 v[174:177], v141 offset:32768
	ds_read_b128 v[178:181], v141 offset:33792
	ds_read_b128 v[182:185], v141 offset:34816
	ds_read_b128 v[186:189], v141 offset:35840
	ds_read_b128 v[190:193], v141 offset:36864
	ds_read_b128 v[198:201], v141 offset:37888
	ds_read_b128 v[202:205], v141 offset:38912
	ds_read_b128 v[206:209], v141 offset:39936
	global_load_lds_dwordx4 v[214:215], off
	v_lshl_add_u64 v[214:215], s[22:23], 0, v[132:133]
	s_mov_b32 m0, s36
	s_nop 0
	global_load_lds_dwordx4 v[214:215], off
	s_waitcnt vmcnt(8)
	s_waitcnt lgkmcnt(0)
	s_barrier
	s_setprio 1
	s_waitcnt lgkmcnt(0)
	v_mfma_f32_16x16x32_bf16 v[126:129], v[142:145], v[174:177], v[126:129]
	v_mfma_f32_16x16x32_bf16 v[126:129], v[146:149], v[178:181], v[126:129]
	v_mfma_f32_16x16x32_bf16 v[122:125], v[150:153], v[174:177], v[122:125]
	v_mfma_f32_16x16x32_bf16 v[122:125], v[154:157], v[178:181], v[122:125]
	v_mfma_f32_16x16x32_bf16 v[110:113], v[142:145], v[182:185], v[110:113]
	v_mfma_f32_16x16x32_bf16 v[110:113], v[146:149], v[186:189], v[110:113]
	v_mfma_f32_16x16x32_bf16 v[106:109], v[150:153], v[182:185], v[106:109]
	v_mfma_f32_16x16x32_bf16 v[106:109], v[154:157], v[186:189], v[106:109]
	v_mfma_f32_16x16x32_bf16 v[94:97], v[142:145], v[190:193], v[94:97]
	v_mfma_f32_16x16x32_bf16 v[94:97], v[146:149], v[198:201], v[94:97]
	v_mfma_f32_16x16x32_bf16 v[90:93], v[150:153], v[190:193], v[90:93]
	v_mfma_f32_16x16x32_bf16 v[90:93], v[154:157], v[198:201], v[90:93]
	v_mfma_f32_16x16x32_bf16 v[78:81], v[142:145], v[202:205], v[78:81]
	v_mfma_f32_16x16x32_bf16 v[78:81], v[146:149], v[206:209], v[78:81]
	v_mfma_f32_16x16x32_bf16 v[74:77], v[150:153], v[202:205], v[74:77]
	v_mfma_f32_16x16x32_bf16 v[74:77], v[154:157], v[206:209], v[74:77]
	s_setprio 0
	s_setprio 1
	v_mfma_f32_16x16x32_bf16 v[118:121], v[158:161], v[174:177], v[118:121]
	v_mfma_f32_16x16x32_bf16 v[118:121], v[162:165], v[178:181], v[118:121]
	v_mfma_f32_16x16x32_bf16 v[114:117], v[166:169], v[174:177], v[114:117]
	v_mfma_f32_16x16x32_bf16 v[114:117], v[170:173], v[178:181], v[114:117]
	v_mfma_f32_16x16x32_bf16 v[102:105], v[158:161], v[182:185], v[102:105]
	v_mfma_f32_16x16x32_bf16 v[102:105], v[162:165], v[186:189], v[102:105]
	v_mfma_f32_16x16x32_bf16 v[98:101], v[166:169], v[182:185], v[98:101]
	v_mfma_f32_16x16x32_bf16 v[98:101], v[170:173], v[186:189], v[98:101]
	v_mfma_f32_16x16x32_bf16 v[86:89], v[158:161], v[190:193], v[86:89]
	v_mfma_f32_16x16x32_bf16 v[86:89], v[162:165], v[198:201], v[86:89]
	v_mfma_f32_16x16x32_bf16 v[82:85], v[166:169], v[190:193], v[82:85]
	v_mfma_f32_16x16x32_bf16 v[82:85], v[170:173], v[198:201], v[82:85]
	v_mfma_f32_16x16x32_bf16 v[70:73], v[158:161], v[202:205], v[70:73]
	v_mfma_f32_16x16x32_bf16 v[70:73], v[162:165], v[206:209], v[70:73]
	v_mfma_f32_16x16x32_bf16 v[66:69], v[166:169], v[202:205], v[66:69]
	v_mfma_f32_16x16x32_bf16 v[66:69], v[170:173], v[206:209], v[66:69]
	s_setprio 0
	s_barrier
	s_add_i32 s22, s44, s31
	v_lshl_add_u64 v[138:139], v[138:139], 0, s[2:3]
	s_mov_b32 m0, s22
	ds_read_b128 v[174:177], v141 offset:49152
	ds_read_b128 v[178:181], v141 offset:50176
	ds_read_b128 v[182:185], v141 offset:51200
	ds_read_b128 v[186:189], v141 offset:52224
	ds_read_b128 v[190:193], v141 offset:53248
	ds_read_b128 v[198:201], v141 offset:54272
	ds_read_b128 v[202:205], v141 offset:55296
	ds_read_b128 v[206:209], v141 offset:56320
	global_load_lds_dwordx4 v[138:139], off
	s_add_i32 m0, s22, 0x2000
	s_add_u32 s18, s18, 0x80080
	v_lshl_add_u64 v[138:139], v[194:195], 0, s[2:3]
	s_addc_u32 s19, s19, 0
	s_add_i32 s22, s47, s31
	global_load_lds_dwordx4 v[138:139], off
	v_lshl_add_u64 v[138:139], s[18:19], 0, v[196:197]
	s_mov_b32 m0, s22
	s_nop 0
	global_load_lds_dwordx4 v[138:139], off
	v_lshl_add_u64 v[138:139], s[18:19], 0, v[130:131]
	s_add_i32 m0, s22, 0x2000
	s_nop 0
	global_load_lds_dwordx4 v[138:139], off
	v_lshl_add_u64 v[138:139], v[210:211], 0, s[2:3]
	s_mov_b32 m0, s37
	s_nop 0
	global_load_lds_dwordx4 v[138:139], off
	v_lshl_add_u64 v[138:139], v[212:213], 0, s[2:3]
	s_mov_b32 m0, s38
	s_nop 0
	global_load_lds_dwordx4 v[138:139], off
	s_waitcnt vmcnt(8)
	s_waitcnt lgkmcnt(0)
	s_barrier
	s_setprio 1
	s_waitcnt lgkmcnt(0)
	v_mfma_f32_16x16x32_bf16 v[62:65], v[142:145], v[174:177], v[62:65]
	v_mfma_f32_16x16x32_bf16 v[62:65], v[146:149], v[178:181], v[62:65]
	v_mfma_f32_16x16x32_bf16 v[58:61], v[150:153], v[174:177], v[58:61]
	v_mfma_f32_16x16x32_bf16 v[58:61], v[154:157], v[178:181], v[58:61]
	v_mfma_f32_16x16x32_bf16 v[46:49], v[142:145], v[182:185], v[46:49]
	v_mfma_f32_16x16x32_bf16 v[46:49], v[146:149], v[186:189], v[46:49]
	v_mfma_f32_16x16x32_bf16 v[42:45], v[150:153], v[182:185], v[42:45]
	v_mfma_f32_16x16x32_bf16 v[42:45], v[154:157], v[186:189], v[42:45]
	v_mfma_f32_16x16x32_bf16 v[30:33], v[142:145], v[190:193], v[30:33]
	v_mfma_f32_16x16x32_bf16 v[30:33], v[146:149], v[198:201], v[30:33]
	v_mfma_f32_16x16x32_bf16 v[26:29], v[150:153], v[190:193], v[26:29]
	v_mfma_f32_16x16x32_bf16 v[26:29], v[154:157], v[198:201], v[26:29]
	v_mfma_f32_16x16x32_bf16 v[14:17], v[142:145], v[202:205], v[14:17]
	v_mfma_f32_16x16x32_bf16 v[14:17], v[146:149], v[206:209], v[14:17]
	v_mfma_f32_16x16x32_bf16 v[10:13], v[150:153], v[202:205], v[10:13]
	v_mfma_f32_16x16x32_bf16 v[10:13], v[154:157], v[206:209], v[10:13]
	s_setprio 0
	s_setprio 1
	v_mfma_f32_16x16x32_bf16 v[54:57], v[158:161], v[174:177], v[54:57]
	v_mfma_f32_16x16x32_bf16 v[54:57], v[162:165], v[178:181], v[54:57]
	v_mfma_f32_16x16x32_bf16 v[50:53], v[166:169], v[174:177], v[50:53]
	v_mfma_f32_16x16x32_bf16 v[50:53], v[170:173], v[178:181], v[50:53]
	v_mfma_f32_16x16x32_bf16 v[38:41], v[158:161], v[182:185], v[38:41]
	v_mfma_f32_16x16x32_bf16 v[38:41], v[162:165], v[186:189], v[38:41]
	v_mfma_f32_16x16x32_bf16 v[34:37], v[166:169], v[182:185], v[34:37]
	v_mfma_f32_16x16x32_bf16 v[34:37], v[170:173], v[186:189], v[34:37]
	v_mfma_f32_16x16x32_bf16 v[22:25], v[158:161], v[190:193], v[22:25]
	v_mfma_f32_16x16x32_bf16 v[22:25], v[162:165], v[198:201], v[22:25]
	v_mfma_f32_16x16x32_bf16 v[18:21], v[166:169], v[190:193], v[18:21]
	v_mfma_f32_16x16x32_bf16 v[18:21], v[170:173], v[198:201], v[18:21]
	v_mfma_f32_16x16x32_bf16 v[6:9], v[158:161], v[202:205], v[6:9]
	v_mfma_f32_16x16x32_bf16 v[6:9], v[162:165], v[206:209], v[6:9]
	v_mfma_f32_16x16x32_bf16 v[2:5], v[166:169], v[202:205], v[2:5]
	v_mfma_f32_16x16x32_bf16 v[2:5], v[170:173], v[206:209], v[2:5]
	s_setprio 0
	s_barrier
	s_cmp_gt_u32 s43, 29
	s_mov_b64 s[18:19], s[20:21]
	s_mov_b32 s22, s43
	s_cbranch_scc1 .Lpeel_exit_w1

.Lpeel_exit_w1:
	v_max_f32_e32 v122, v122, v122
	s_lshl_b32 s1, s41, 5
	v_max_f32_e32 v122, 0, v122
	v_max_f32_e32 v123, v123, v123
	v_max_f32_e32 v124, v124, v124
	s_add_i32 s12, s1, s42
	v_mul_f32_e32 v142, v122, v122
	v_max_f32_e32 v122, v127, v127
	v_max_f32_e32 v123, 0, v123
	v_max_f32_e32 v124, 0, v124
	s_ashr_i32 s13, s12, 31
	v_max_f32_e32 v126, v126, v126
	v_max_f32_e32 v122, 0, v122
	v_mul_f32_e32 v127, v123, v123
	v_max_f32_e32 v123, v128, v128
	v_mul_f32_e32 v128, v124, v124
	v_max_f32_e32 v124, v129, v129
	v_max_f32_e32 v125, v125, v125
	s_lshl_b64 s[12:13], s[12:13], 17
	v_max_f32_e32 v126, 0, v126
	v_mul_f32_e32 v122, v122, v122
	v_max_f32_e32 v123, 0, v123
	v_max_f32_e32 v124, 0, v124
	v_max_f32_e32 v125, 0, v125
	v_max_f32_e32 v114, v114, v114
	v_lshl_add_u64 v[138:139], v[136:137], 0, s[12:13]
	v_mul_f32_e32 v126, v126, v126
	v_mul_f32_e32 v123, v123, v123
	v_mul_f32_e32 v124, v124, v124
	v_mul_f32_e32 v125, v125, v125
	v_cvt_pk_bf16_f32 v122, v126, v122
	v_max_f32_e32 v114, 0, v114
	v_max_f32_e32 v115, v115, v115
	v_max_f32_e32 v116, v116, v116
	v_cvt_pk_bf16_f32 v123, v123, v124
	v_cvt_pk_bf16_f32 v124, v142, v127
	v_cvt_pk_bf16_f32 v125, v128, v125
	global_store_dwordx4 v[138:139], v[122:125], off
	v_max_f32_e32 v115, 0, v115
	v_max_f32_e32 v116, 0, v116
	v_mul_f32_e32 v122, v114, v114
	v_max_f32_e32 v114, v119, v119
	v_max_f32_e32 v118, v118, v118
	v_max_f32_e32 v114, 0, v114
	v_mul_f32_e32 v119, v115, v115
	v_max_f32_e32 v115, v120, v120
	v_mul_f32_e32 v120, v116, v116
	v_max_f32_e32 v116, v121, v121
	v_max_f32_e32 v117, v117, v117
	v_max_f32_e32 v118, 0, v118
	v_mul_f32_e32 v114, v114, v114
	v_max_f32_e32 v115, 0, v115
	v_max_f32_e32 v116, 0, v116
	v_max_f32_e32 v117, 0, v117
	v_max_f32_e32 v106, v106, v106
	v_mul_f32_e32 v118, v118, v118
	v_mul_f32_e32 v115, v115, v115
	v_mul_f32_e32 v116, v116, v116
	v_mul_f32_e32 v117, v117, v117
	v_cvt_pk_bf16_f32 v114, v118, v114
	v_max_f32_e32 v106, 0, v106
	v_max_f32_e32 v107, v107, v107
	v_max_f32_e32 v108, v108, v108
	v_cvt_pk_bf16_f32 v115, v115, v116
	v_cvt_pk_bf16_f32 v116, v122, v119
	v_cvt_pk_bf16_f32 v117, v120, v117
	global_store_dwordx4 v[138:139], v[114:117], off offset:256
	v_max_f32_e32 v110, v110, v110
	v_max_f32_e32 v107, 0, v107
	v_mul_f32_e32 v114, v106, v106
	v_max_f32_e32 v106, v111, v111
	v_max_f32_e32 v108, 0, v108
	v_max_f32_e32 v110, 0, v110
	v_max_f32_e32 v106, 0, v106
	v_mul_f32_e32 v111, v107, v107
	v_max_f32_e32 v107, v112, v112
	v_mul_f32_e32 v112, v108, v108
	v_max_f32_e32 v108, v113, v113
	v_mul_f32_e32 v110, v110, v110
	v_mul_f32_e32 v106, v106, v106
	v_max_f32_e32 v107, 0, v107
	v_max_f32_e32 v108, 0, v108
	v_max_f32_e32 v109, v109, v109
	s_movk_i32 s1, 0x2000
	v_mul_f32_e32 v107, v107, v107
	v_max_f32_e32 v109, 0, v109
	v_mul_f32_e32 v108, v108, v108
	v_cvt_pk_bf16_f32 v106, v110, v106
	v_add_co_u32_e32 v110, vcc, s1, v138
	v_max_f32_e32 v98, v98, v98
	v_mul_f32_e32 v109, v109, v109
	v_cvt_pk_bf16_f32 v107, v107, v108
	v_cvt_pk_bf16_f32 v108, v114, v111
	v_addc_co_u32_e32 v111, vcc, 0, v139, vcc
	v_max_f32_e32 v98, 0, v98
	v_max_f32_e32 v99, v99, v99
	v_max_f32_e32 v100, v100, v100
	v_cvt_pk_bf16_f32 v109, v112, v109
	global_store_dwordx4 v[110:111], v[106:109], off
	v_max_f32_e32 v99, 0, v99
	v_max_f32_e32 v100, 0, v100
	v_mul_f32_e32 v106, v98, v98
	v_max_f32_e32 v98, v103, v103
	v_max_f32_e32 v102, v102, v102
	v_max_f32_e32 v98, 0, v98
	v_mul_f32_e32 v103, v99, v99
	v_max_f32_e32 v99, v104, v104
	v_mul_f32_e32 v104, v100, v100
	v_max_f32_e32 v100, v105, v105
	v_max_f32_e32 v101, v101, v101
	v_max_f32_e32 v102, 0, v102
	v_mul_f32_e32 v98, v98, v98
	v_max_f32_e32 v99, 0, v99
	v_max_f32_e32 v100, 0, v100
	v_max_f32_e32 v101, 0, v101
	v_max_f32_e32 v90, v90, v90
	v_mul_f32_e32 v102, v102, v102
	v_mul_f32_e32 v99, v99, v99
	v_mul_f32_e32 v100, v100, v100
	v_mul_f32_e32 v101, v101, v101
	v_cvt_pk_bf16_f32 v98, v102, v98
	v_max_f32_e32 v90, 0, v90
	v_max_f32_e32 v91, v91, v91
	v_max_f32_e32 v92, v92, v92
	v_cvt_pk_bf16_f32 v99, v99, v100
	v_cvt_pk_bf16_f32 v100, v106, v103
	v_cvt_pk_bf16_f32 v101, v104, v101
	global_store_dwordx4 v[110:111], v[98:101], off offset:256
	v_max_f32_e32 v94, v94, v94
	v_max_f32_e32 v91, 0, v91
	v_mul_f32_e32 v98, v90, v90
	v_max_f32_e32 v90, v95, v95
	v_max_f32_e32 v92, 0, v92
	v_max_f32_e32 v94, 0, v94
	v_max_f32_e32 v90, 0, v90
	v_mul_f32_e32 v95, v91, v91
	v_max_f32_e32 v91, v96, v96
	v_mul_f32_e32 v96, v92, v92
	v_max_f32_e32 v92, v97, v97
	v_mul_f32_e32 v94, v94, v94
	v_mul_f32_e32 v90, v90, v90
	v_max_f32_e32 v91, 0, v91
	v_max_f32_e32 v92, 0, v92
	v_max_f32_e32 v93, v93, v93
	s_movk_i32 s1, 0x4000
	v_mul_f32_e32 v91, v91, v91
	v_max_f32_e32 v93, 0, v93
	v_mul_f32_e32 v92, v92, v92
	v_cvt_pk_bf16_f32 v90, v94, v90
	v_add_co_u32_e32 v94, vcc, s1, v138
	v_max_f32_e32 v82, v82, v82
	v_mul_f32_e32 v93, v93, v93
	v_cvt_pk_bf16_f32 v91, v91, v92
	v_cvt_pk_bf16_f32 v92, v98, v95
	v_addc_co_u32_e32 v95, vcc, 0, v139, vcc
	v_max_f32_e32 v82, 0, v82
	v_max_f32_e32 v83, v83, v83
	v_max_f32_e32 v84, v84, v84
	v_cvt_pk_bf16_f32 v93, v96, v93
	global_store_dwordx4 v[94:95], v[90:93], off
	v_max_f32_e32 v83, 0, v83
	v_max_f32_e32 v84, 0, v84
	v_mul_f32_e32 v90, v82, v82
	v_max_f32_e32 v82, v87, v87
	v_max_f32_e32 v86, v86, v86
	v_max_f32_e32 v82, 0, v82
	v_mul_f32_e32 v87, v83, v83
	v_max_f32_e32 v83, v88, v88
	v_mul_f32_e32 v88, v84, v84
	v_max_f32_e32 v84, v89, v89
	v_max_f32_e32 v85, v85, v85
	v_max_f32_e32 v86, 0, v86
	v_mul_f32_e32 v82, v82, v82
	v_max_f32_e32 v83, 0, v83
	v_max_f32_e32 v84, 0, v84
	v_max_f32_e32 v85, 0, v85
	v_max_f32_e32 v74, v74, v74
	v_mul_f32_e32 v86, v86, v86
	v_mul_f32_e32 v83, v83, v83
	v_mul_f32_e32 v84, v84, v84
	v_mul_f32_e32 v85, v85, v85
	v_cvt_pk_bf16_f32 v82, v86, v82
	v_max_f32_e32 v74, 0, v74
	v_max_f32_e32 v75, v75, v75
	v_max_f32_e32 v76, v76, v76
	v_cvt_pk_bf16_f32 v83, v83, v84
	v_cvt_pk_bf16_f32 v84, v90, v87
	v_cvt_pk_bf16_f32 v85, v88, v85
	global_store_dwordx4 v[94:95], v[82:85], off offset:256
	v_max_f32_e32 v78, v78, v78
	v_max_f32_e32 v75, 0, v75
	v_mul_f32_e32 v82, v74, v74
	v_max_f32_e32 v74, v79, v79
	v_max_f32_e32 v76, 0, v76
	v_max_f32_e32 v78, 0, v78
	v_max_f32_e32 v74, 0, v74
	v_mul_f32_e32 v79, v75, v75
	v_max_f32_e32 v75, v80, v80
	v_mul_f32_e32 v80, v76, v76
	v_max_f32_e32 v76, v81, v81
	v_mul_f32_e32 v78, v78, v78
	v_mul_f32_e32 v74, v74, v74
	v_max_f32_e32 v75, 0, v75
	v_max_f32_e32 v76, 0, v76
	v_max_f32_e32 v77, v77, v77
	s_movk_i32 s1, 0x6000
	v_mul_f32_e32 v75, v75, v75
	v_max_f32_e32 v77, 0, v77
	v_mul_f32_e32 v76, v76, v76
	v_cvt_pk_bf16_f32 v74, v78, v74
	v_add_co_u32_e32 v78, vcc, s1, v138
	v_max_f32_e32 v66, v66, v66
	v_mul_f32_e32 v77, v77, v77
	v_cvt_pk_bf16_f32 v75, v75, v76
	v_cvt_pk_bf16_f32 v76, v82, v79
	v_addc_co_u32_e32 v79, vcc, 0, v139, vcc
	v_max_f32_e32 v66, 0, v66
	v_max_f32_e32 v67, v67, v67
	v_max_f32_e32 v68, v68, v68
	v_cvt_pk_bf16_f32 v77, v80, v77
	global_store_dwordx4 v[78:79], v[74:77], off
	v_max_f32_e32 v67, 0, v67
	v_max_f32_e32 v68, 0, v68
	v_mul_f32_e32 v74, v66, v66
	v_max_f32_e32 v66, v71, v71
	v_max_f32_e32 v70, v70, v70
	v_max_f32_e32 v66, 0, v66
	v_mul_f32_e32 v71, v67, v67
	v_max_f32_e32 v67, v72, v72
	v_mul_f32_e32 v72, v68, v68
	v_max_f32_e32 v68, v73, v73
	v_max_f32_e32 v69, v69, v69
	v_max_f32_e32 v70, 0, v70
	v_mul_f32_e32 v66, v66, v66
	v_max_f32_e32 v67, 0, v67
	v_max_f32_e32 v68, 0, v68
	v_max_f32_e32 v69, 0, v69
	v_max_f32_e32 v58, v58, v58
	v_mul_f32_e32 v70, v70, v70
	v_mul_f32_e32 v67, v67, v67
	v_mul_f32_e32 v68, v68, v68
	v_mul_f32_e32 v69, v69, v69
	v_cvt_pk_bf16_f32 v66, v70, v66
	v_max_f32_e32 v58, 0, v58
	v_max_f32_e32 v59, v59, v59
	v_max_f32_e32 v60, v60, v60
	v_cvt_pk_bf16_f32 v67, v67, v68
	v_cvt_pk_bf16_f32 v68, v74, v71
	v_cvt_pk_bf16_f32 v69, v72, v69
	global_store_dwordx4 v[78:79], v[66:69], off offset:256
	v_max_f32_e32 v62, v62, v62
	v_max_f32_e32 v59, 0, v59
	v_mul_f32_e32 v66, v58, v58
	v_max_f32_e32 v58, v63, v63
	v_max_f32_e32 v60, 0, v60
	v_max_f32_e32 v62, 0, v62
	v_max_f32_e32 v58, 0, v58
	v_mul_f32_e32 v63, v59, v59
	v_max_f32_e32 v59, v64, v64
	v_mul_f32_e32 v64, v60, v60
	v_max_f32_e32 v60, v65, v65
	v_mul_f32_e32 v62, v62, v62
	v_mul_f32_e32 v58, v58, v58
	v_max_f32_e32 v59, 0, v59
	v_max_f32_e32 v60, 0, v60
	v_max_f32_e32 v61, v61, v61
	s_mov_b32 s1, 0x10000
	v_mul_f32_e32 v59, v59, v59
	v_max_f32_e32 v61, 0, v61
	v_mul_f32_e32 v60, v60, v60
	v_cvt_pk_bf16_f32 v58, v62, v58
	v_add_co_u32_e32 v62, vcc, s1, v138
	v_max_f32_e32 v50, v50, v50
	v_mul_f32_e32 v61, v61, v61
	v_cvt_pk_bf16_f32 v59, v59, v60
	v_cvt_pk_bf16_f32 v60, v66, v63
	v_addc_co_u32_e32 v63, vcc, 0, v139, vcc
	v_max_f32_e32 v50, 0, v50
	v_max_f32_e32 v51, v51, v51
	v_max_f32_e32 v52, v52, v52
	v_cvt_pk_bf16_f32 v61, v64, v61
	global_store_dwordx4 v[62:63], v[58:61], off
	v_max_f32_e32 v51, 0, v51
	v_max_f32_e32 v52, 0, v52
	v_mul_f32_e32 v58, v50, v50
	v_max_f32_e32 v50, v55, v55
	v_max_f32_e32 v54, v54, v54
	v_max_f32_e32 v50, 0, v50
	v_mul_f32_e32 v55, v51, v51
	v_max_f32_e32 v51, v56, v56
	v_mul_f32_e32 v56, v52, v52
	v_max_f32_e32 v52, v57, v57
	v_max_f32_e32 v53, v53, v53
	v_max_f32_e32 v54, 0, v54
	v_mul_f32_e32 v50, v50, v50
	v_max_f32_e32 v51, 0, v51
	v_max_f32_e32 v52, 0, v52
	v_max_f32_e32 v53, 0, v53
	v_max_f32_e32 v42, v42, v42
	v_mul_f32_e32 v54, v54, v54
	v_mul_f32_e32 v51, v51, v51
	v_mul_f32_e32 v52, v52, v52
	v_mul_f32_e32 v53, v53, v53
	v_cvt_pk_bf16_f32 v50, v54, v50
	v_max_f32_e32 v42, 0, v42
	v_max_f32_e32 v43, v43, v43
	v_max_f32_e32 v44, v44, v44
	v_cvt_pk_bf16_f32 v51, v51, v52
	v_cvt_pk_bf16_f32 v52, v58, v55
	v_cvt_pk_bf16_f32 v53, v56, v53
	global_store_dwordx4 v[62:63], v[50:53], off offset:256
	v_max_f32_e32 v46, v46, v46
	v_max_f32_e32 v43, 0, v43
	v_mul_f32_e32 v50, v42, v42
	v_max_f32_e32 v42, v47, v47
	v_max_f32_e32 v44, 0, v44
	v_max_f32_e32 v46, 0, v46
	v_max_f32_e32 v42, 0, v42
	v_mul_f32_e32 v47, v43, v43
	v_max_f32_e32 v43, v48, v48
	v_mul_f32_e32 v48, v44, v44
	v_max_f32_e32 v44, v49, v49
	v_mul_f32_e32 v46, v46, v46
	v_mul_f32_e32 v42, v42, v42
	v_max_f32_e32 v43, 0, v43
	v_max_f32_e32 v44, 0, v44
	v_max_f32_e32 v45, v45, v45
	s_mov_b32 s1, 0x12000
	v_mul_f32_e32 v43, v43, v43
	v_max_f32_e32 v45, 0, v45
	v_mul_f32_e32 v44, v44, v44
	v_cvt_pk_bf16_f32 v42, v46, v42
	v_add_co_u32_e32 v46, vcc, s1, v138
	v_max_f32_e32 v34, v34, v34
	v_mul_f32_e32 v45, v45, v45
	v_cvt_pk_bf16_f32 v43, v43, v44
	v_cvt_pk_bf16_f32 v44, v50, v47
	v_addc_co_u32_e32 v47, vcc, 0, v139, vcc
	v_max_f32_e32 v34, 0, v34
	v_max_f32_e32 v35, v35, v35
	v_max_f32_e32 v36, v36, v36
	v_cvt_pk_bf16_f32 v45, v48, v45
	global_store_dwordx4 v[46:47], v[42:45], off
	v_max_f32_e32 v35, 0, v35
	v_max_f32_e32 v36, 0, v36
	v_mul_f32_e32 v42, v34, v34
	v_max_f32_e32 v34, v39, v39
	v_max_f32_e32 v38, v38, v38
	v_max_f32_e32 v34, 0, v34
	v_mul_f32_e32 v39, v35, v35
	v_max_f32_e32 v35, v40, v40
	v_mul_f32_e32 v40, v36, v36
	v_max_f32_e32 v36, v41, v41
	v_max_f32_e32 v37, v37, v37
	v_max_f32_e32 v38, 0, v38
	v_mul_f32_e32 v34, v34, v34
	v_max_f32_e32 v35, 0, v35
	v_max_f32_e32 v36, 0, v36
	v_max_f32_e32 v37, 0, v37
	v_max_f32_e32 v26, v26, v26
	v_mul_f32_e32 v38, v38, v38
	v_mul_f32_e32 v35, v35, v35
	v_mul_f32_e32 v36, v36, v36
	v_mul_f32_e32 v37, v37, v37
	v_cvt_pk_bf16_f32 v34, v38, v34
	v_max_f32_e32 v26, 0, v26
	v_max_f32_e32 v27, v27, v27
	v_max_f32_e32 v28, v28, v28
	v_cvt_pk_bf16_f32 v35, v35, v36
	v_cvt_pk_bf16_f32 v36, v42, v39
	v_cvt_pk_bf16_f32 v37, v40, v37
	global_store_dwordx4 v[46:47], v[34:37], off offset:256
	v_max_f32_e32 v30, v30, v30
	v_max_f32_e32 v27, 0, v27
	v_mul_f32_e32 v34, v26, v26
	v_max_f32_e32 v26, v31, v31
	v_max_f32_e32 v28, 0, v28
	v_max_f32_e32 v30, 0, v30
	v_max_f32_e32 v26, 0, v26
	v_mul_f32_e32 v31, v27, v27
	v_max_f32_e32 v27, v32, v32
	v_mul_f32_e32 v32, v28, v28
	v_max_f32_e32 v28, v33, v33
	v_mul_f32_e32 v30, v30, v30
	v_mul_f32_e32 v26, v26, v26
	v_max_f32_e32 v27, 0, v27
	v_max_f32_e32 v28, 0, v28
	v_max_f32_e32 v29, v29, v29
	s_mov_b32 s1, 0x14000
	v_mul_f32_e32 v27, v27, v27
	v_max_f32_e32 v29, 0, v29
	v_mul_f32_e32 v28, v28, v28
	v_cvt_pk_bf16_f32 v26, v30, v26
	v_add_co_u32_e32 v30, vcc, s1, v138
	v_max_f32_e32 v18, v18, v18
	v_mul_f32_e32 v29, v29, v29
	v_cvt_pk_bf16_f32 v27, v27, v28
	v_cvt_pk_bf16_f32 v28, v34, v31
	v_addc_co_u32_e32 v31, vcc, 0, v139, vcc
	v_max_f32_e32 v18, 0, v18
	v_max_f32_e32 v19, v19, v19
	v_max_f32_e32 v20, v20, v20
	v_cvt_pk_bf16_f32 v29, v32, v29
	global_store_dwordx4 v[30:31], v[26:29], off
	v_max_f32_e32 v19, 0, v19
	v_max_f32_e32 v20, 0, v20
	v_mul_f32_e32 v26, v18, v18
	v_max_f32_e32 v18, v23, v23
	v_max_f32_e32 v22, v22, v22
	v_max_f32_e32 v18, 0, v18
	v_mul_f32_e32 v23, v19, v19
	v_max_f32_e32 v19, v24, v24
	v_mul_f32_e32 v24, v20, v20
	v_max_f32_e32 v20, v25, v25
	v_max_f32_e32 v21, v21, v21
	v_max_f32_e32 v22, 0, v22
	v_mul_f32_e32 v18, v18, v18
	v_max_f32_e32 v19, 0, v19
	v_max_f32_e32 v20, 0, v20
	v_max_f32_e32 v21, 0, v21
	v_max_f32_e32 v10, v10, v10
	v_mul_f32_e32 v22, v22, v22
	v_mul_f32_e32 v19, v19, v19
	v_mul_f32_e32 v20, v20, v20
	v_mul_f32_e32 v21, v21, v21
	v_cvt_pk_bf16_f32 v18, v22, v18
	v_max_f32_e32 v10, 0, v10
	v_max_f32_e32 v11, v11, v11
	v_max_f32_e32 v12, v12, v12
	v_cvt_pk_bf16_f32 v19, v19, v20
	v_cvt_pk_bf16_f32 v20, v26, v23
	v_cvt_pk_bf16_f32 v21, v24, v21
	global_store_dwordx4 v[30:31], v[18:21], off offset:256
	v_max_f32_e32 v14, v14, v14
	v_max_f32_e32 v11, 0, v11
	v_mul_f32_e32 v18, v10, v10
	v_max_f32_e32 v10, v15, v15
	v_max_f32_e32 v12, 0, v12
	v_max_f32_e32 v14, 0, v14
	v_max_f32_e32 v10, 0, v10
	v_mul_f32_e32 v15, v11, v11
	v_max_f32_e32 v11, v16, v16
	v_mul_f32_e32 v16, v12, v12
	v_max_f32_e32 v12, v17, v17
	v_mul_f32_e32 v14, v14, v14
	v_mul_f32_e32 v10, v10, v10
	v_max_f32_e32 v11, 0, v11
	v_max_f32_e32 v12, 0, v12
	v_max_f32_e32 v13, v13, v13
	s_mov_b32 s1, 0x16000
	v_mul_f32_e32 v11, v11, v11
	v_max_f32_e32 v13, 0, v13
	v_mul_f32_e32 v12, v12, v12
	v_cvt_pk_bf16_f32 v10, v14, v10
	v_add_co_u32_e32 v14, vcc, s1, v138
	v_max_f32_e32 v2, v2, v2
	v_max_f32_e32 v3, v3, v3
	v_max_f32_e32 v4, v4, v4
	v_mul_f32_e32 v13, v13, v13
	v_cvt_pk_bf16_f32 v11, v11, v12
	v_cvt_pk_bf16_f32 v12, v18, v15
	v_addc_co_u32_e32 v15, vcc, 0, v139, vcc
	v_max_f32_e32 v2, 0, v2
	v_max_f32_e32 v3, 0, v3
	v_max_f32_e32 v4, 0, v4
	v_cvt_pk_bf16_f32 v13, v16, v13
	global_store_dwordx4 v[14:15], v[10:13], off
	v_max_f32_e32 v5, v5, v5
	v_max_f32_e32 v6, v6, v6
	v_mul_f32_e32 v10, v2, v2
	v_max_f32_e32 v2, v7, v7
	v_mul_f32_e32 v7, v3, v3
	v_max_f32_e32 v3, v8, v8
	v_mul_f32_e32 v8, v4, v4
	v_max_f32_e32 v4, v9, v9
	v_max_f32_e32 v2, 0, v2
	v_max_f32_e32 v3, 0, v3
	v_max_f32_e32 v4, 0, v4
	v_max_f32_e32 v5, 0, v5
	v_max_f32_e32 v6, 0, v6
	v_mul_f32_e32 v2, v2, v2
	v_mul_f32_e32 v3, v3, v3
	v_mul_f32_e32 v4, v4, v4
	v_mul_f32_e32 v5, v5, v5
	s_and_b64 vcc, exec, s[4:5]
	s_mov_b32 s42, s0
	s_mov_b32 s41, s6
	s_mov_b64 s[18:19], s[8:9]
	s_mov_b64 s[12:13], s[10:11]
	v_mul_f32_e32 v6, v6, v6
	v_cvt_pk_bf16_f32 v2, v6, v2
	v_cvt_pk_bf16_f32 v3, v3, v4
	v_cvt_pk_bf16_f32 v4, v10, v7
	v_cvt_pk_bf16_f32 v5, v8, v5
	global_store_dwordx4 v[14:15], v[2:5], off offset:256
	s_cbranch_vccz .LBB0_960
	s_waitcnt vmcnt(0)
	s_cmpk_gt_u32 s26, 0xff
	s_cbranch_scc1 .LBB0_967
	s_barrier

.LBB0_1029:
	s_add_u32 s58, s28, 0x100
	s_addc_u32 s59, s29, 0
	s_mov_b32 s60, 2
	s_mov_b64 s[28:29], 0
	s_add_i32 s30, s60, -2
	s_lshr_b32 s44, s30, 2
	s_lshl_b64 s[34:35], s[44:45], 17
	s_lshr_b32 s44, s60, 2
	s_and_b32 s61, s28, 0x100
	s_lshl_b64 s[30:31], s[44:45], 17
	s_add_u32 s44, s26, s30
	s_addc_u32 s62, s27, s31
	s_add_u32 s30, s28, 0x100
	s_addc_u32 s31, s29, 0
	s_and_b32 s63, s30, 0x100
	s_add_u32 s44, s44, s63
	s_addc_u32 s62, s62, 0
	s_add_u32 s28, s58, s28
	s_addc_u32 s29, s59, s29
	s_add_i32 s64, 0, 0x10000
	s_add_u32 s63, s26, s34
	s_addc_u32 s65, s27, s35
	s_cmp_eq_u32 s57, s60
	s_cselect_b32 s35, s23, s62
	s_cselect_b32 s34, s22, s44
	s_cselect_b32 s29, s25, s29
	s_cselect_b32 s28, s24, s28
	s_add_i32 s44, 0, 0x14000
	v_add_u32_e32 v152, s64, v137
	v_add_u32_e32 v168, s44, v137
	ds_read_b128 v[140:143], v152
	ds_read_b128 v[144:147], v152 offset:1024
	ds_read_b128 v[148:151], v152 offset:2048
	ds_read_b128 v[152:155], v152 offset:3072
	ds_read_b128 v[156:159], v168
	ds_read_b128 v[160:163], v168 offset:1024
	ds_read_b128 v[164:167], v168 offset:2048
	ds_read_b128 v[168:171], v168 offset:3072
	s_add_u32 s61, s63, s61
	s_addc_u32 s63, s65, 0
	s_add_u32 s62, s61, 0x10080
	s_addc_u32 s63, s63, 0
	v_lshl_add_u64 v[206:207], s[62:63], 0, v[130:131]
	s_add_i32 m0, s33, 0xc000
	ds_read_b128 v[172:175], v139
	ds_read_b128 v[176:179], v139 offset:1024
	ds_read_b128 v[180:183], v139 offset:2048
	ds_read_b128 v[184:187], v139 offset:3072
	ds_read_b128 v[188:191], v139 offset:4096
	ds_read_b128 v[192:195], v139 offset:5120
	ds_read_b128 v[198:201], v139 offset:6144
	ds_read_b128 v[202:205], v139 offset:7168
	global_load_lds_dwordx4 v[206:207], off
	v_lshl_add_u64 v[206:207], s[62:63], 0, v[132:133]
	s_add_i32 m0, s33, 0xe000
	s_nop 0
	global_load_lds_dwordx4 v[206:207], off
	s_waitcnt vmcnt(8)
	s_waitcnt lgkmcnt(0)
	s_barrier
	s_setprio 1
	s_waitcnt lgkmcnt(0)
	v_mfma_f32_16x16x32_bf16 v[126:129], v[140:143], v[172:175], 0
	v_mfma_f32_16x16x32_bf16 v[126:129], v[144:147], v[176:179], v[126:129]
	v_mfma_f32_16x16x32_bf16 v[122:125], v[148:151], v[172:175], 0
	v_mfma_f32_16x16x32_bf16 v[122:125], v[152:155], v[176:179], v[122:125]
	v_mfma_f32_16x16x32_bf16 v[110:113], v[140:143], v[180:183], 0
	v_mfma_f32_16x16x32_bf16 v[110:113], v[144:147], v[184:187], v[110:113]
	v_mfma_f32_16x16x32_bf16 v[106:109], v[148:151], v[180:183], 0
	v_mfma_f32_16x16x32_bf16 v[106:109], v[152:155], v[184:187], v[106:109]
	v_mfma_f32_16x16x32_bf16 v[94:97], v[140:143], v[188:191], 0
	v_mfma_f32_16x16x32_bf16 v[94:97], v[144:147], v[192:195], v[94:97]
	v_mfma_f32_16x16x32_bf16 v[90:93], v[148:151], v[188:191], 0
	v_mfma_f32_16x16x32_bf16 v[90:93], v[152:155], v[192:195], v[90:93]
	v_mfma_f32_16x16x32_bf16 v[78:81], v[140:143], v[198:201], 0
	v_mfma_f32_16x16x32_bf16 v[78:81], v[144:147], v[202:205], v[78:81]
	v_mfma_f32_16x16x32_bf16 v[74:77], v[148:151], v[198:201], 0
	v_mfma_f32_16x16x32_bf16 v[74:77], v[152:155], v[202:205], v[74:77]
	s_setprio 0
	s_setprio 1
	v_mfma_f32_16x16x32_bf16 v[118:121], v[156:159], v[172:175], 0
	v_mfma_f32_16x16x32_bf16 v[118:121], v[160:163], v[176:179], v[118:121]
	v_mfma_f32_16x16x32_bf16 v[114:117], v[164:167], v[172:175], 0
	v_mfma_f32_16x16x32_bf16 v[114:117], v[168:171], v[176:179], v[114:117]
	v_mfma_f32_16x16x32_bf16 v[102:105], v[156:159], v[180:183], 0
	v_mfma_f32_16x16x32_bf16 v[102:105], v[160:163], v[184:187], v[102:105]
	v_mfma_f32_16x16x32_bf16 v[98:101], v[164:167], v[180:183], 0
	v_mfma_f32_16x16x32_bf16 v[98:101], v[168:171], v[184:187], v[98:101]
	v_mfma_f32_16x16x32_bf16 v[86:89], v[156:159], v[188:191], 0
	v_mfma_f32_16x16x32_bf16 v[86:89], v[160:163], v[192:195], v[86:89]
	v_mfma_f32_16x16x32_bf16 v[82:85], v[164:167], v[188:191], 0
	v_mfma_f32_16x16x32_bf16 v[82:85], v[168:171], v[192:195], v[82:85]
	v_mfma_f32_16x16x32_bf16 v[70:73], v[156:159], v[198:201], 0
	v_mfma_f32_16x16x32_bf16 v[70:73], v[160:163], v[202:205], v[70:73]
	v_mfma_f32_16x16x32_bf16 v[66:69], v[164:167], v[198:201], 0
	v_mfma_f32_16x16x32_bf16 v[66:69], v[168:171], v[202:205], v[66:69]
	s_setprio 0
	s_barrier
	s_add_i32 s61, s64, s9
	v_lshl_add_u64 v[206:207], s[28:29], 0, v[196:197]
	s_mov_b32 m0, s61
	ds_read_b128 v[172:175], v139 offset:16384
	ds_read_b128 v[176:179], v139 offset:17408
	ds_read_b128 v[180:183], v139 offset:18432
	ds_read_b128 v[184:187], v139 offset:19456
	ds_read_b128 v[188:191], v139 offset:20480
	ds_read_b128 v[192:195], v139 offset:21504
	ds_read_b128 v[198:201], v139 offset:22528
	ds_read_b128 v[202:205], v139 offset:23552
	global_load_lds_dwordx4 v[206:207], off
	s_add_i32 m0, s61, 0x2000
	s_add_u32 s62, s28, 0x204000
	v_lshl_add_u64 v[208:209], s[28:29], 0, v[134:135]
	s_addc_u32 s63, s29, 0
	s_add_i32 s44, s44, s9
	global_load_lds_dwordx4 v[208:209], off
	v_lshl_add_u64 v[210:211], s[62:63], 0, v[196:197]
	s_mov_b32 m0, s44
	v_lshl_add_u64 v[212:213], s[34:35], 0, v[132:133]
	global_load_lds_dwordx4 v[210:211], off
	v_lshl_add_u64 v[210:211], s[62:63], 0, v[134:135]
	s_add_i32 m0, s44, 0x2000
	s_nop 0
	global_load_lds_dwordx4 v[210:211], off
	v_lshl_add_u64 v[210:211], s[34:35], 0, v[130:131]
	s_mov_b32 m0, s33
	s_nop 0
	global_load_lds_dwordx4 v[210:211], off
	s_mov_b32 m0, s36
	s_nop 0
	global_load_lds_dwordx4 v[212:213], off
	s_waitcnt vmcnt(8)
	s_waitcnt lgkmcnt(0)
	s_barrier
	s_setprio 1
	s_waitcnt lgkmcnt(0)
	v_mfma_f32_16x16x32_bf16 v[62:65], v[140:143], v[172:175], 0
	v_mfma_f32_16x16x32_bf16 v[62:65], v[144:147], v[176:179], v[62:65]
	v_mfma_f32_16x16x32_bf16 v[58:61], v[148:151], v[172:175], 0
	v_mfma_f32_16x16x32_bf16 v[58:61], v[152:155], v[176:179], v[58:61]
	v_mfma_f32_16x16x32_bf16 v[46:49], v[140:143], v[180:183], 0
	v_mfma_f32_16x16x32_bf16 v[46:49], v[144:147], v[184:187], v[46:49]
	v_mfma_f32_16x16x32_bf16 v[42:45], v[148:151], v[180:183], 0
	v_mfma_f32_16x16x32_bf16 v[42:45], v[152:155], v[184:187], v[42:45]
	v_mfma_f32_16x16x32_bf16 v[30:33], v[140:143], v[188:191], 0
	v_mfma_f32_16x16x32_bf16 v[30:33], v[144:147], v[192:195], v[30:33]
	v_mfma_f32_16x16x32_bf16 v[26:29], v[148:151], v[188:191], 0
	v_mfma_f32_16x16x32_bf16 v[26:29], v[152:155], v[192:195], v[26:29]
	v_mfma_f32_16x16x32_bf16 v[14:17], v[140:143], v[198:201], 0
	v_mfma_f32_16x16x32_bf16 v[14:17], v[144:147], v[202:205], v[14:17]
	v_mfma_f32_16x16x32_bf16 v[10:13], v[148:151], v[198:201], 0
	v_mfma_f32_16x16x32_bf16 v[10:13], v[152:155], v[202:205], v[10:13]
	s_setprio 0
	s_setprio 1
	v_mfma_f32_16x16x32_bf16 v[54:57], v[156:159], v[172:175], 0
	v_mfma_f32_16x16x32_bf16 v[54:57], v[160:163], v[176:179], v[54:57]
	v_mfma_f32_16x16x32_bf16 v[50:53], v[164:167], v[172:175], 0
	v_mfma_f32_16x16x32_bf16 v[50:53], v[168:171], v[176:179], v[50:53]
	v_mfma_f32_16x16x32_bf16 v[38:41], v[156:159], v[180:183], 0
	v_mfma_f32_16x16x32_bf16 v[38:41], v[160:163], v[184:187], v[38:41]
	v_mfma_f32_16x16x32_bf16 v[34:37], v[164:167], v[180:183], 0
	v_mfma_f32_16x16x32_bf16 v[34:37], v[168:171], v[184:187], v[34:37]
	v_mfma_f32_16x16x32_bf16 v[22:25], v[156:159], v[188:191], 0
	v_mfma_f32_16x16x32_bf16 v[22:25], v[160:163], v[192:195], v[22:25]
	v_mfma_f32_16x16x32_bf16 v[18:21], v[164:167], v[188:191], 0
	v_mfma_f32_16x16x32_bf16 v[18:21], v[168:171], v[192:195], v[18:21]
	v_mfma_f32_16x16x32_bf16 v[6:9], v[156:159], v[198:201], 0
	v_mfma_f32_16x16x32_bf16 v[6:9], v[160:163], v[202:205], v[6:9]
	v_mfma_f32_16x16x32_bf16 v[2:5], v[164:167], v[198:201], 0
	v_mfma_f32_16x16x32_bf16 v[2:5], v[168:171], v[202:205], v[2:5]
	s_setprio 0
	s_barrier
	s_add_i32 s44, 0, 0x18000
	s_add_i32 s61, 0, 0x1c000
	v_add_u32_e32 v152, s44, v137
	v_add_u32_e32 v168, s61, v137
	ds_read_b128 v[140:143], v152
	ds_read_b128 v[144:147], v152 offset:1024
	ds_read_b128 v[148:151], v152 offset:2048
	ds_read_b128 v[152:155], v152 offset:3072
	ds_read_b128 v[156:159], v168
	ds_read_b128 v[160:163], v168 offset:1024
	ds_read_b128 v[164:167], v168 offset:2048
	ds_read_b128 v[168:171], v168 offset:3072
	s_add_u32 s34, s34, 0x10000
	s_addc_u32 s35, s35, 0
	s_mov_b32 m0, s37
	v_lshl_add_u64 v[214:215], s[34:35], 0, v[130:131]
	ds_read_b128 v[172:175], v139 offset:32768
	ds_read_b128 v[176:179], v139 offset:33792
	ds_read_b128 v[180:183], v139 offset:34816
	ds_read_b128 v[184:187], v139 offset:35840
	ds_read_b128 v[188:191], v139 offset:36864
	ds_read_b128 v[192:195], v139 offset:37888
	ds_read_b128 v[198:201], v139 offset:38912
	ds_read_b128 v[202:205], v139 offset:39936
	global_load_lds_dwordx4 v[214:215], off
	v_lshl_add_u64 v[214:215], s[34:35], 0, v[132:133]
	s_mov_b32 m0, s38
	s_nop 0
	global_load_lds_dwordx4 v[214:215], off
	s_waitcnt vmcnt(8)
	s_waitcnt lgkmcnt(0)
	s_barrier
	s_setprio 1
	s_waitcnt lgkmcnt(0)
	v_mfma_f32_16x16x32_bf16 v[126:129], v[140:143], v[172:175], v[126:129]
	v_mfma_f32_16x16x32_bf16 v[126:129], v[144:147], v[176:179], v[126:129]
	v_mfma_f32_16x16x32_bf16 v[122:125], v[148:151], v[172:175], v[122:125]
	v_mfma_f32_16x16x32_bf16 v[122:125], v[152:155], v[176:179], v[122:125]
	v_mfma_f32_16x16x32_bf16 v[110:113], v[140:143], v[180:183], v[110:113]
	v_mfma_f32_16x16x32_bf16 v[110:113], v[144:147], v[184:187], v[110:113]
	v_mfma_f32_16x16x32_bf16 v[106:109], v[148:151], v[180:183], v[106:109]
	v_mfma_f32_16x16x32_bf16 v[106:109], v[152:155], v[184:187], v[106:109]
	v_mfma_f32_16x16x32_bf16 v[94:97], v[140:143], v[188:191], v[94:97]
	v_mfma_f32_16x16x32_bf16 v[94:97], v[144:147], v[192:195], v[94:97]
	v_mfma_f32_16x16x32_bf16 v[90:93], v[148:151], v[188:191], v[90:93]
	v_mfma_f32_16x16x32_bf16 v[90:93], v[152:155], v[192:195], v[90:93]
	v_mfma_f32_16x16x32_bf16 v[78:81], v[140:143], v[198:201], v[78:81]
	v_mfma_f32_16x16x32_bf16 v[78:81], v[144:147], v[202:205], v[78:81]
	v_mfma_f32_16x16x32_bf16 v[74:77], v[148:151], v[198:201], v[74:77]
	v_mfma_f32_16x16x32_bf16 v[74:77], v[152:155], v[202:205], v[74:77]
	s_setprio 0
	s_setprio 1
	v_mfma_f32_16x16x32_bf16 v[118:121], v[156:159], v[172:175], v[118:121]
	v_mfma_f32_16x16x32_bf16 v[118:121], v[160:163], v[176:179], v[118:121]
	v_mfma_f32_16x16x32_bf16 v[114:117], v[164:167], v[172:175], v[114:117]
	v_mfma_f32_16x16x32_bf16 v[114:117], v[168:171], v[176:179], v[114:117]
	v_mfma_f32_16x16x32_bf16 v[102:105], v[156:159], v[180:183], v[102:105]
	v_mfma_f32_16x16x32_bf16 v[102:105], v[160:163], v[184:187], v[102:105]
	v_mfma_f32_16x16x32_bf16 v[98:101], v[164:167], v[180:183], v[98:101]
	v_mfma_f32_16x16x32_bf16 v[98:101], v[168:171], v[184:187], v[98:101]
	v_mfma_f32_16x16x32_bf16 v[86:89], v[156:159], v[188:191], v[86:89]
	v_mfma_f32_16x16x32_bf16 v[86:89], v[160:163], v[192:195], v[86:89]
	v_mfma_f32_16x16x32_bf16 v[82:85], v[164:167], v[188:191], v[82:85]
	v_mfma_f32_16x16x32_bf16 v[82:85], v[168:171], v[192:195], v[82:85]
	v_mfma_f32_16x16x32_bf16 v[70:73], v[156:159], v[198:201], v[70:73]
	v_mfma_f32_16x16x32_bf16 v[70:73], v[160:163], v[202:205], v[70:73]
	v_mfma_f32_16x16x32_bf16 v[66:69], v[164:167], v[198:201], v[66:69]
	v_mfma_f32_16x16x32_bf16 v[66:69], v[168:171], v[202:205], v[66:69]
	s_setprio 0
	s_barrier
	s_add_i32 s34, s44, s9
	v_lshl_add_u64 v[206:207], v[206:207], 0, s[2:3]
	s_mov_b32 m0, s34
	ds_read_b128 v[172:175], v139 offset:49152
	ds_read_b128 v[176:179], v139 offset:50176
	ds_read_b128 v[180:183], v139 offset:51200
	ds_read_b128 v[184:187], v139 offset:52224
	ds_read_b128 v[188:191], v139 offset:53248
	ds_read_b128 v[192:195], v139 offset:54272
	ds_read_b128 v[198:201], v139 offset:55296
	ds_read_b128 v[202:205], v139 offset:56320
	global_load_lds_dwordx4 v[206:207], off
	s_add_i32 m0, s34, 0x2000
	s_add_u32 s28, s28, 0x204080
	v_lshl_add_u64 v[206:207], v[208:209], 0, s[2:3]
	s_addc_u32 s29, s29, 0
	s_add_i32 s34, s61, s9
	global_load_lds_dwordx4 v[206:207], off
	v_lshl_add_u64 v[206:207], s[28:29], 0, v[196:197]
	s_mov_b32 m0, s34
	s_nop 0
	global_load_lds_dwordx4 v[206:207], off
	v_lshl_add_u64 v[206:207], s[28:29], 0, v[134:135]
	s_add_i32 m0, s34, 0x2000
	s_nop 0
	global_load_lds_dwordx4 v[206:207], off
	v_lshl_add_u64 v[206:207], v[210:211], 0, s[2:3]
	s_mov_b32 m0, s47
	s_nop 0
	global_load_lds_dwordx4 v[206:207], off
	v_lshl_add_u64 v[206:207], v[212:213], 0, s[2:3]
	s_mov_b32 m0, s49
	s_nop 0
	global_load_lds_dwordx4 v[206:207], off
	s_waitcnt vmcnt(8)
	s_waitcnt lgkmcnt(0)
	s_barrier
	s_setprio 1
	s_waitcnt lgkmcnt(0)
	v_mfma_f32_16x16x32_bf16 v[62:65], v[140:143], v[172:175], v[62:65]
	v_mfma_f32_16x16x32_bf16 v[62:65], v[144:147], v[176:179], v[62:65]
	v_mfma_f32_16x16x32_bf16 v[58:61], v[148:151], v[172:175], v[58:61]
	v_mfma_f32_16x16x32_bf16 v[58:61], v[152:155], v[176:179], v[58:61]
	v_mfma_f32_16x16x32_bf16 v[46:49], v[140:143], v[180:183], v[46:49]
	v_mfma_f32_16x16x32_bf16 v[46:49], v[144:147], v[184:187], v[46:49]
	v_mfma_f32_16x16x32_bf16 v[42:45], v[148:151], v[180:183], v[42:45]
	v_mfma_f32_16x16x32_bf16 v[42:45], v[152:155], v[184:187], v[42:45]
	v_mfma_f32_16x16x32_bf16 v[30:33], v[140:143], v[188:191], v[30:33]
	v_mfma_f32_16x16x32_bf16 v[30:33], v[144:147], v[192:195], v[30:33]
	v_mfma_f32_16x16x32_bf16 v[26:29], v[148:151], v[188:191], v[26:29]
	v_mfma_f32_16x16x32_bf16 v[26:29], v[152:155], v[192:195], v[26:29]
	v_mfma_f32_16x16x32_bf16 v[14:17], v[140:143], v[198:201], v[14:17]
	v_mfma_f32_16x16x32_bf16 v[14:17], v[144:147], v[202:205], v[14:17]
	v_mfma_f32_16x16x32_bf16 v[10:13], v[148:151], v[198:201], v[10:13]
	v_mfma_f32_16x16x32_bf16 v[10:13], v[152:155], v[202:205], v[10:13]
	s_setprio 0
	s_setprio 1
	v_mfma_f32_16x16x32_bf16 v[54:57], v[156:159], v[172:175], v[54:57]
	v_mfma_f32_16x16x32_bf16 v[54:57], v[160:163], v[176:179], v[54:57]
	v_mfma_f32_16x16x32_bf16 v[50:53], v[164:167], v[172:175], v[50:53]
	v_mfma_f32_16x16x32_bf16 v[50:53], v[168:171], v[176:179], v[50:53]
	v_mfma_f32_16x16x32_bf16 v[38:41], v[156:159], v[180:183], v[38:41]
	v_mfma_f32_16x16x32_bf16 v[38:41], v[160:163], v[184:187], v[38:41]
	v_mfma_f32_16x16x32_bf16 v[34:37], v[164:167], v[180:183], v[34:37]
	v_mfma_f32_16x16x32_bf16 v[34:37], v[168:171], v[184:187], v[34:37]
	v_mfma_f32_16x16x32_bf16 v[22:25], v[156:159], v[188:191], v[22:25]
	v_mfma_f32_16x16x32_bf16 v[22:25], v[160:163], v[192:195], v[22:25]
	v_mfma_f32_16x16x32_bf16 v[18:21], v[164:167], v[188:191], v[18:21]
	v_mfma_f32_16x16x32_bf16 v[18:21], v[168:171], v[192:195], v[18:21]
	v_mfma_f32_16x16x32_bf16 v[6:9], v[156:159], v[198:201], v[6:9]
	v_mfma_f32_16x16x32_bf16 v[6:9], v[160:163], v[202:205], v[6:9]
	v_mfma_f32_16x16x32_bf16 v[2:5], v[164:167], v[198:201], v[2:5]
	v_mfma_f32_16x16x32_bf16 v[2:5], v[168:171], v[202:205], v[2:5]
	s_setprio 0
	s_barrier
	s_add_i32 s34, s60, 2
	s_cmp_ge_i32 s60, s57
	s_mov_b64 s[28:29], s[30:31]
	s_mov_b32 s60, s34
	s_cbranch_scc1 .Lpeel_exit_w2

.Lpeel_exit_w2:
	v_readlane_b32 s58, v254, 51
	v_readlane_b32 s59, v254, 52
	s_and_b64 vcc, exec, s[10:11]
	s_cbranch_vccz .LBB0_1033
